# S5 pass2 recurrence: complex multiply-add as two packed f32 FMAs per step, all per-step LDS reads issued up front, per-step LDS waits removed
# speedup vs baseline: 1.0057x; 1.0041x over previous
.LBB0_1787:
	s_or_b64 exec, exec, s[0:1]
	s_movk_i32 s1, 0x3200
	v_mul_lo_u32 v72, v82, s1
	v_add_u32_e32 v81, 0, v72
	s_waitcnt vmcnt(0) lgkmcnt(0)
	v_mfma_f32_16x16x32_bf16 v[84:87], v[0:3], v[32:35], 0
	v_mul_u32_u24_e32 v72, 0x210, v83
	v_lshlrev_b32_e32 v73, 2, v79
	v_lshlrev_b32_e32 v72, 2, v72
	v_mfma_f32_16x16x32_bf16 v[96:99], v[0:3], v[28:31], 0
	v_add3_u32 v73, v81, v73, v72
	v_add_u32_e32 v74, 0x400, v73
	s_nop 5
	ds_write2_b32 v73, v84, v96 offset1:16
	ds_write2_b32 v73, v85, v97 offset0:132 offset1:148
	ds_write2_b32 v74, v86, v98 offset0:8 offset1:24
	ds_write2_b32 v74, v87, v99 offset0:140 offset1:156
	v_mfma_f32_16x16x32_bf16 v[82:85], v[0:3], v[40:43], 0
	v_lshl_add_u32 v75, v78, 2, v81
	s_cmp_gt_i32 s9, 3
	s_cselect_b32 s0, 0x87, 3
	v_mfma_f32_16x16x32_bf16 v[86:89], v[0:3], v[36:39], 0
	s_nop 7
	ds_write2_b32 v73, v82, v86 offset0:32 offset1:48
	ds_write2_b32 v73, v83, v87 offset0:164 offset1:180
	ds_write2_b32 v74, v84, v88 offset0:40 offset1:56
	ds_write2_b32 v74, v85, v89 offset0:172 offset1:188
	v_mfma_f32_16x16x32_bf16 v[82:85], v[0:3], v[48:51], 0
	s_sub_i32 s0, s0, s9
	v_mul_u32_u24_e32 v94, 0x110, v79
	v_add_u32_e32 v79, 64, v75
	v_mfma_f32_16x16x32_bf16 v[86:89], v[0:3], v[44:47], 0
	s_nop 7
	ds_write2_b32 v73, v82, v86 offset0:64 offset1:80
	ds_write2_b32 v73, v83, v87 offset0:196 offset1:212
	ds_write2_b32 v74, v84, v88 offset0:72 offset1:88
	ds_write2_b32 v74, v85, v89 offset0:204 offset1:220
	v_mfma_f32_16x16x32_bf16 v[82:85], v[0:3], v[56:59], 0
	v_add_u32_e32 v86, 0x90, v75
	v_add_u32_e32 v87, 0xa0, v75
	v_add_u32_e32 v88, 0xb0, v75
	v_mfma_f32_16x16x32_bf16 v[0:3], v[0:3], v[52:55], 0
	s_nop 7
	ds_write2_b32 v73, v82, v0 offset0:96 offset1:112
	ds_write2_b32 v73, v83, v1 offset0:228 offset1:244
	ds_write2_b32 v74, v84, v2 offset0:104 offset1:120
	ds_write2_b32 v74, v85, v3 offset0:236 offset1:252
	v_lshlrev_b32_e32 v0, 1, v78
	s_waitcnt vmcnt(0) lgkmcnt(0)
	v_sub_u32_e32 v72, v75, v0
	ds_read2st64_b32 v[0:1], v75 offset1:1
	ds_read2_b32 v[140:141], v75 offset0:132 offset1:196
	v_add_u32_e32 v142, 32, v75
	ds_read2st64_b32 v[144:145], v142 offset0:4 offset1:5
	v_add_u32_e32 v143, 48, v75
	ds_read2st64_b32 v[146:147], v143 offset0:6 offset1:7
	ds_read2st64_b32 v[148:149], v79 offset0:8 offset1:9
	v_add_u32_e32 v150, 0x50, v75
	ds_read2st64_b32 v[152:153], v150 offset0:10 offset1:11
	v_add_u32_e32 v151, 0x60, v75
	ds_read2st64_b32 v[154:155], v151 offset0:12 offset1:13
	v_add_u32_e32 v156, 0x70, v75
	ds_read2st64_b32 v[158:159], v156 offset0:14 offset1:15
	v_add_u32_e32 v157, 0x80, v75
	ds_read2st64_b32 v[160:161], v157 offset0:16 offset1:17
	ds_read2st64_b32 v[162:163], v86 offset0:18 offset1:19
	ds_read2st64_b32 v[164:165], v87 offset0:20 offset1:21
	ds_read2st64_b32 v[166:167], v88 offset0:22 offset1:23
	v_add_u32_e32 v168, 0xc0, v75
	ds_read2st64_b32 v[170:171], v168 offset0:24 offset1:25
	v_add_u32_e32 v169, 0xd0, v75
	ds_read2st64_b32 v[172:173], v169 offset0:26 offset1:27
	v_add_u32_e32 v174, 0xe0, v75
	ds_read2st64_b32 v[176:177], v174 offset0:28 offset1:29
	v_add_u32_e32 v175, 0xf0, v75
	ds_read2st64_b32 v[178:179], v175 offset0:30 offset1:31
	v_mov_b32_e32 v186, v70
	v_mov_b32_e32 v187, v71
	v_add_u32_e32 v78, 48, v75
	v_add_u32_e32 v82, 0x50, v75
	s_waitcnt lgkmcnt(0)
	v_pk_fma_f32 v[184:185], v[66:67], v[186:187], v[0:1] op_sel:[1,1,0] op_sel_hi:[1,0,1] neg_lo:[1,0,0]
	v_pk_fma_f32 v[188:189], v[66:67], v[186:187], v[184:185] op_sel_hi:[0,1,1]
	v_cvt_pk_bf16_f32 v190, v188, v189
	ds_write_b16 v72, v190 offset:8448
	ds_write_b16_d16_hi v72, v190 offset:8576
	v_add_u32_e32 v71, 32, v75
	v_add_u32_e32 v83, 0x60, v75
	v_pk_fma_f32 v[184:185], v[66:67], v[188:189], v[140:141] op_sel:[1,1,0] op_sel_hi:[1,0,1] neg_lo:[1,0,0]
	v_pk_fma_f32 v[186:187], v[66:67], v[188:189], v[184:185] op_sel_hi:[0,1,1]
	v_cvt_pk_bf16_f32 v190, v186, v187
	ds_write_b16 v72, v190 offset:8720
	ds_write_b16_d16_hi v72, v190 offset:8848
	v_add_u32_e32 v84, 0x70, v75
	v_add_u32_e32 v85, 0x80, v75
	v_pk_fma_f32 v[184:185], v[66:67], v[186:187], v[144:145] op_sel:[1,1,0] op_sel_hi:[1,0,1] neg_lo:[1,0,0]
	v_pk_fma_f32 v[188:189], v[66:67], v[186:187], v[184:185] op_sel_hi:[0,1,1]
	v_cvt_pk_bf16_f32 v190, v188, v189
	ds_write_b16 v72, v190 offset:8992
	ds_write_b16_d16_hi v72, v190 offset:9120
	v_add_u32_e32 v89, 0xc0, v75
	v_add_u32_e32 v91, 0xd0, v75
	v_pk_fma_f32 v[184:185], v[66:67], v[188:189], v[146:147] op_sel:[1,1,0] op_sel_hi:[1,0,1] neg_lo:[1,0,0]
	v_pk_fma_f32 v[186:187], v[66:67], v[188:189], v[184:185] op_sel_hi:[0,1,1]
	v_cvt_pk_bf16_f32 v190, v186, v187
	ds_write_b16 v72, v190 offset:9264
	ds_write_b16_d16_hi v72, v190 offset:9392
	v_add_u32_e32 v92, 0xe0, v75
	v_add_u32_e32 v93, 0xf0, v75
	v_pk_fma_f32 v[184:185], v[66:67], v[186:187], v[148:149] op_sel:[1,1,0] op_sel_hi:[1,0,1] neg_lo:[1,0,0]
	v_pk_fma_f32 v[188:189], v[66:67], v[186:187], v[184:185] op_sel_hi:[0,1,1]
	v_cvt_pk_bf16_f32 v190, v188, v189
	ds_write_b16 v72, v190 offset:9536
	ds_write_b16_d16_hi v72, v190 offset:9664
	v_mfma_f32_16x16x32_bf16 v[98:101], v[4:7], v[28:31], 0
	s_or_b32 s1, s2, 0x84
	v_pk_fma_f32 v[184:185], v[66:67], v[188:189], v[152:153] op_sel:[1,1,0] op_sel_hi:[1,0,1] neg_lo:[1,0,0]
	v_pk_fma_f32 v[186:187], v[66:67], v[188:189], v[184:185] op_sel_hi:[0,1,1]
	v_cvt_pk_bf16_f32 v190, v186, v187
	ds_write_b16 v72, v190 offset:9808
	ds_write_b16_d16_hi v72, v190 offset:9936
	s_ashr_i32 s2, s0, 31
	v_pk_fma_f32 v[184:185], v[66:67], v[186:187], v[154:155] op_sel:[1,1,0] op_sel_hi:[1,0,1] neg_lo:[1,0,0]
	v_pk_fma_f32 v[188:189], v[66:67], v[186:187], v[184:185] op_sel_hi:[0,1,1]
	v_cvt_pk_bf16_f32 v190, v188, v189
	ds_write_b16 v72, v190 offset:10080
	ds_write_b16_d16_hi v72, v190 offset:10208
	v_pk_fma_f32 v[184:185], v[66:67], v[188:189], v[158:159] op_sel:[1,1,0] op_sel_hi:[1,0,1] neg_lo:[1,0,0]
	v_pk_fma_f32 v[186:187], v[66:67], v[188:189], v[184:185] op_sel_hi:[0,1,1]
	v_cvt_pk_bf16_f32 v190, v186, v187
	ds_write_b16 v72, v190 offset:10352
	ds_write_b16_d16_hi v72, v190 offset:10480
	v_pk_fma_f32 v[184:185], v[66:67], v[186:187], v[160:161] op_sel:[1,1,0] op_sel_hi:[1,0,1] neg_lo:[1,0,0]
	v_pk_fma_f32 v[188:189], v[66:67], v[186:187], v[184:185] op_sel_hi:[0,1,1]
	v_cvt_pk_bf16_f32 v190, v188, v189
	ds_write_b16 v72, v190 offset:10624
	ds_write_b16_d16_hi v72, v190 offset:10752
	v_pk_fma_f32 v[184:185], v[66:67], v[188:189], v[162:163] op_sel:[1,1,0] op_sel_hi:[1,0,1] neg_lo:[1,0,0]
	v_pk_fma_f32 v[186:187], v[66:67], v[188:189], v[184:185] op_sel_hi:[0,1,1]
	v_cvt_pk_bf16_f32 v190, v186, v187
	ds_write_b16 v72, v190 offset:10896
	ds_write_b16_d16_hi v72, v190 offset:11024
	v_pk_fma_f32 v[184:185], v[66:67], v[186:187], v[164:165] op_sel:[1,1,0] op_sel_hi:[1,0,1] neg_lo:[1,0,0]
	v_pk_fma_f32 v[188:189], v[66:67], v[186:187], v[184:185] op_sel_hi:[0,1,1]
	v_cvt_pk_bf16_f32 v190, v188, v189
	ds_write_b16 v72, v190 offset:11168
	ds_write_b16_d16_hi v72, v190 offset:11296
	v_pk_fma_f32 v[184:185], v[66:67], v[188:189], v[166:167] op_sel:[1,1,0] op_sel_hi:[1,0,1] neg_lo:[1,0,0]
	v_pk_fma_f32 v[186:187], v[66:67], v[188:189], v[184:185] op_sel_hi:[0,1,1]
	v_cvt_pk_bf16_f32 v190, v186, v187
	ds_write_b16 v72, v190 offset:11440
	ds_write_b16_d16_hi v72, v190 offset:11568
	v_pk_fma_f32 v[184:185], v[66:67], v[186:187], v[170:171] op_sel:[1,1,0] op_sel_hi:[1,0,1] neg_lo:[1,0,0]
	v_pk_fma_f32 v[188:189], v[66:67], v[186:187], v[184:185] op_sel_hi:[0,1,1]
	v_cvt_pk_bf16_f32 v190, v188, v189
	ds_write_b16 v72, v190 offset:11712
	ds_write_b16_d16_hi v72, v190 offset:11840
	v_pk_fma_f32 v[184:185], v[66:67], v[188:189], v[172:173] op_sel:[1,1,0] op_sel_hi:[1,0,1] neg_lo:[1,0,0]
	v_pk_fma_f32 v[186:187], v[66:67], v[188:189], v[184:185] op_sel_hi:[0,1,1]
	v_cvt_pk_bf16_f32 v190, v186, v187
	ds_write_b16 v72, v190 offset:11984
	ds_write_b16_d16_hi v72, v190 offset:12112
	v_pk_fma_f32 v[184:185], v[66:67], v[186:187], v[176:177] op_sel:[1,1,0] op_sel_hi:[1,0,1] neg_lo:[1,0,0]
	v_pk_fma_f32 v[188:189], v[66:67], v[186:187], v[184:185] op_sel_hi:[0,1,1]
	v_cvt_pk_bf16_f32 v190, v188, v189
	ds_write_b16 v72, v190 offset:12256
	ds_write_b16_d16_hi v72, v190 offset:12384
	v_pk_fma_f32 v[184:185], v[66:67], v[188:189], v[178:179] op_sel:[1,1,0] op_sel_hi:[1,0,1] neg_lo:[1,0,0]
	v_pk_fma_f32 v[186:187], v[66:67], v[188:189], v[184:185] op_sel_hi:[0,1,1]
	v_mov_b32_e32 v102, v186
	v_mov_b32_e32 v103, v187
	v_cvt_pk_bf16_f32 v190, v186, v187
	ds_write_b16 v72, v190 offset:12528
	ds_write_b16_d16_hi v72, v190 offset:12656
	v_add3_u32 v70, v81, v128, v94
	s_waitcnt vmcnt(0) lgkmcnt(0)
	ds_read_b128 v[0:3], v70 offset:8448
	ds_read_b128 v[94:97], v70 offset:8512
	s_waitcnt lgkmcnt(1)
	v_mfma_f32_16x16x32_bf16 v[0:3], v[0:3], v[24:27], 0
	s_waitcnt lgkmcnt(0)
	v_mfma_f32_16x16x32_bf16 v[0:3], v[94:97], v[20:23], v[0:3]
	ds_read_b128 v[94:97], v70 offset:8576
	s_waitcnt lgkmcnt(0)
	v_mfma_f32_16x16x32_bf16 v[0:3], v[94:97], v[16:19], v[0:3]
	ds_read_b128 v[94:97], v70 offset:8640
	s_waitcnt lgkmcnt(0)
	v_mfma_f32_16x16x32_bf16 v[0:3], v[94:97], v[12:15], v[0:3]
	v_mfma_f32_16x16x32_bf16 v[94:97], v[4:7], v[32:35], 0
	s_nop 7
	ds_write2_b32 v73, v94, v98 offset1:16
	ds_write2_b32 v73, v95, v99 offset0:132 offset1:148
	ds_write2_b32 v74, v96, v100 offset0:8 offset1:24
	ds_write2_b32 v74, v97, v101 offset0:140 offset1:156
	v_mfma_f32_16x16x32_bf16 v[94:97], v[4:7], v[40:43], 0
	v_mfma_f32_16x16x32_bf16 v[98:101], v[4:7], v[36:39], 0
	s_nop 7
	ds_write2_b32 v73, v94, v98 offset0:32 offset1:48
	ds_write2_b32 v73, v95, v99 offset0:164 offset1:180
	ds_write2_b32 v74, v96, v100 offset0:40 offset1:56
	ds_write2_b32 v74, v97, v101 offset0:172 offset1:188
	v_mfma_f32_16x16x32_bf16 v[94:97], v[4:7], v[48:51], 0
	v_mfma_f32_16x16x32_bf16 v[98:101], v[4:7], v[44:47], 0
	s_nop 7
	ds_write2_b32 v73, v94, v98 offset0:64 offset1:80
	ds_write2_b32 v73, v95, v99 offset0:196 offset1:212
	ds_write2_b32 v74, v96, v100 offset0:72 offset1:88
	ds_write2_b32 v74, v97, v101 offset0:204 offset1:220
	v_mfma_f32_16x16x32_bf16 v[94:97], v[4:7], v[56:59], 0
	v_mfma_f32_16x16x32_bf16 v[4:7], v[4:7], v[52:55], 0
	s_nop 7
	ds_write2_b32 v73, v94, v4 offset0:96 offset1:112
	ds_write2_b32 v73, v95, v5 offset0:228 offset1:244
	ds_write2_b32 v74, v96, v6 offset0:104 offset1:120
	ds_write2_b32 v74, v97, v7 offset0:236 offset1:252
	s_waitcnt vmcnt(0) lgkmcnt(0)
	ds_read2st64_b32 v[4:5], v75 offset1:1
	ds_read2_b32 v[140:141], v75 offset0:132 offset1:196
	ds_read2st64_b32 v[142:143], v71 offset0:4 offset1:5
	ds_read2st64_b32 v[144:145], v78 offset0:6 offset1:7
	ds_read2st64_b32 v[146:147], v79 offset0:8 offset1:9
	ds_read2st64_b32 v[148:149], v82 offset0:10 offset1:11
	ds_read2st64_b32 v[150:151], v83 offset0:12 offset1:13
	ds_read2st64_b32 v[152:153], v84 offset0:14 offset1:15
	ds_read2st64_b32 v[154:155], v85 offset0:16 offset1:17
	ds_read2st64_b32 v[156:157], v86 offset0:18 offset1:19
	ds_read2st64_b32 v[158:159], v87 offset0:20 offset1:21
	ds_read2st64_b32 v[160:161], v88 offset0:22 offset1:23
	ds_read2st64_b32 v[162:163], v89 offset0:24 offset1:25
	ds_read2st64_b32 v[164:165], v91 offset0:26 offset1:27
	ds_read2st64_b32 v[166:167], v92 offset0:28 offset1:29
	ds_read2st64_b32 v[168:169], v93 offset0:30 offset1:31
	v_mov_b32_e32 v186, v102
	v_mov_b32_e32 v187, v103
	v_mfma_f32_16x16x32_bf16 v[98:101], v[8:11], v[28:31], 0
	s_waitcnt lgkmcnt(0)
	v_pk_fma_f32 v[184:185], v[66:67], v[186:187], v[4:5] op_sel:[1,1,0] op_sel_hi:[1,0,1] neg_lo:[1,0,0]
	v_pk_fma_f32 v[188:189], v[66:67], v[186:187], v[184:185] op_sel_hi:[0,1,1]
	v_cvt_pk_bf16_f32 v190, v188, v189
	ds_write_b16 v72, v190 offset:8448
	ds_write_b16_d16_hi v72, v190 offset:8576
	v_mfma_f32_16x16x32_bf16 v[28:31], v[60:63], v[28:31], 0
	v_pk_fma_f32 v[184:185], v[66:67], v[188:189], v[140:141] op_sel:[1,1,0] op_sel_hi:[1,0,1] neg_lo:[1,0,0]
	v_pk_fma_f32 v[186:187], v[66:67], v[188:189], v[184:185] op_sel_hi:[0,1,1]
	v_cvt_pk_bf16_f32 v190, v186, v187
	ds_write_b16 v72, v190 offset:8720
	ds_write_b16_d16_hi v72, v190 offset:8848
	v_pk_fma_f32 v[184:185], v[66:67], v[186:187], v[142:143] op_sel:[1,1,0] op_sel_hi:[1,0,1] neg_lo:[1,0,0]
	v_pk_fma_f32 v[188:189], v[66:67], v[186:187], v[184:185] op_sel_hi:[0,1,1]
	v_cvt_pk_bf16_f32 v190, v188, v189
	ds_write_b16 v72, v190 offset:8992
	ds_write_b16_d16_hi v72, v190 offset:9120
	v_pk_fma_f32 v[184:185], v[66:67], v[188:189], v[144:145] op_sel:[1,1,0] op_sel_hi:[1,0,1] neg_lo:[1,0,0]
	v_pk_fma_f32 v[186:187], v[66:67], v[188:189], v[184:185] op_sel_hi:[0,1,1]
	v_cvt_pk_bf16_f32 v190, v186, v187
	ds_write_b16 v72, v190 offset:9264
	ds_write_b16_d16_hi v72, v190 offset:9392
	v_pk_fma_f32 v[184:185], v[66:67], v[186:187], v[146:147] op_sel:[1,1,0] op_sel_hi:[1,0,1] neg_lo:[1,0,0]
	v_pk_fma_f32 v[188:189], v[66:67], v[186:187], v[184:185] op_sel_hi:[0,1,1]
	v_cvt_pk_bf16_f32 v190, v188, v189
	ds_write_b16 v72, v190 offset:9536
	ds_write_b16_d16_hi v72, v190 offset:9664
	v_pk_fma_f32 v[184:185], v[66:67], v[188:189], v[148:149] op_sel:[1,1,0] op_sel_hi:[1,0,1] neg_lo:[1,0,0]
	v_pk_fma_f32 v[186:187], v[66:67], v[188:189], v[184:185] op_sel_hi:[0,1,1]
	v_cvt_pk_bf16_f32 v190, v186, v187
	ds_write_b16 v72, v190 offset:9808
	ds_write_b16_d16_hi v72, v190 offset:9936
	v_pk_fma_f32 v[184:185], v[66:67], v[186:187], v[150:151] op_sel:[1,1,0] op_sel_hi:[1,0,1] neg_lo:[1,0,0]
	v_pk_fma_f32 v[188:189], v[66:67], v[186:187], v[184:185] op_sel_hi:[0,1,1]
	v_cvt_pk_bf16_f32 v190, v188, v189
	ds_write_b16 v72, v190 offset:10080
	ds_write_b16_d16_hi v72, v190 offset:10208
	v_pk_fma_f32 v[184:185], v[66:67], v[188:189], v[152:153] op_sel:[1,1,0] op_sel_hi:[1,0,1] neg_lo:[1,0,0]
	v_pk_fma_f32 v[186:187], v[66:67], v[188:189], v[184:185] op_sel_hi:[0,1,1]
	v_cvt_pk_bf16_f32 v190, v186, v187
	ds_write_b16 v72, v190 offset:10352
	ds_write_b16_d16_hi v72, v190 offset:10480
	v_pk_fma_f32 v[184:185], v[66:67], v[186:187], v[154:155] op_sel:[1,1,0] op_sel_hi:[1,0,1] neg_lo:[1,0,0]
	v_pk_fma_f32 v[188:189], v[66:67], v[186:187], v[184:185] op_sel_hi:[0,1,1]
	v_cvt_pk_bf16_f32 v190, v188, v189
	ds_write_b16 v72, v190 offset:10624
	ds_write_b16_d16_hi v72, v190 offset:10752
	v_pk_fma_f32 v[184:185], v[66:67], v[188:189], v[156:157] op_sel:[1,1,0] op_sel_hi:[1,0,1] neg_lo:[1,0,0]
	v_pk_fma_f32 v[186:187], v[66:67], v[188:189], v[184:185] op_sel_hi:[0,1,1]
	v_cvt_pk_bf16_f32 v190, v186, v187
	ds_write_b16 v72, v190 offset:10896
	ds_write_b16_d16_hi v72, v190 offset:11024
	v_pk_fma_f32 v[184:185], v[66:67], v[186:187], v[158:159] op_sel:[1,1,0] op_sel_hi:[1,0,1] neg_lo:[1,0,0]
	v_pk_fma_f32 v[188:189], v[66:67], v[186:187], v[184:185] op_sel_hi:[0,1,1]
	v_cvt_pk_bf16_f32 v190, v188, v189
	ds_write_b16 v72, v190 offset:11168
	ds_write_b16_d16_hi v72, v190 offset:11296
	v_pk_fma_f32 v[184:185], v[66:67], v[188:189], v[160:161] op_sel:[1,1,0] op_sel_hi:[1,0,1] neg_lo:[1,0,0]
	v_pk_fma_f32 v[186:187], v[66:67], v[188:189], v[184:185] op_sel_hi:[0,1,1]
	v_cvt_pk_bf16_f32 v190, v186, v187
	ds_write_b16 v72, v190 offset:11440
	ds_write_b16_d16_hi v72, v190 offset:11568
	v_pk_fma_f32 v[184:185], v[66:67], v[186:187], v[162:163] op_sel:[1,1,0] op_sel_hi:[1,0,1] neg_lo:[1,0,0]
	v_pk_fma_f32 v[188:189], v[66:67], v[186:187], v[184:185] op_sel_hi:[0,1,1]
	v_cvt_pk_bf16_f32 v190, v188, v189
	ds_write_b16 v72, v190 offset:11712
	ds_write_b16_d16_hi v72, v190 offset:11840
	v_pk_fma_f32 v[184:185], v[66:67], v[188:189], v[164:165] op_sel:[1,1,0] op_sel_hi:[1,0,1] neg_lo:[1,0,0]
	v_pk_fma_f32 v[186:187], v[66:67], v[188:189], v[184:185] op_sel_hi:[0,1,1]
	v_cvt_pk_bf16_f32 v190, v186, v187
	ds_write_b16 v72, v190 offset:11984
	ds_write_b16_d16_hi v72, v190 offset:12112
	v_pk_fma_f32 v[184:185], v[66:67], v[186:187], v[166:167] op_sel:[1,1,0] op_sel_hi:[1,0,1] neg_lo:[1,0,0]
	v_pk_fma_f32 v[188:189], v[66:67], v[186:187], v[184:185] op_sel_hi:[0,1,1]
	v_cvt_pk_bf16_f32 v190, v188, v189
	ds_write_b16 v72, v190 offset:12256
	ds_write_b16_d16_hi v72, v190 offset:12384
	v_pk_fma_f32 v[184:185], v[66:67], v[188:189], v[168:169] op_sel:[1,1,0] op_sel_hi:[1,0,1] neg_lo:[1,0,0]
	v_pk_fma_f32 v[186:187], v[66:67], v[188:189], v[184:185] op_sel_hi:[0,1,1]
	v_mov_b32_e32 v102, v186
	v_mov_b32_e32 v103, v187
	v_cvt_pk_bf16_f32 v190, v186, v187
	ds_write_b16 v72, v190 offset:12528
	ds_write_b16_d16_hi v72, v190 offset:12656
	s_waitcnt vmcnt(0) lgkmcnt(0)
	ds_read_b128 v[4:7], v70 offset:8448
	ds_read_b128 v[94:97], v70 offset:8512
	s_waitcnt lgkmcnt(1)
	v_mfma_f32_16x16x32_bf16 v[4:7], v[4:7], v[24:27], 0
	s_waitcnt lgkmcnt(0)
	v_mfma_f32_16x16x32_bf16 v[4:7], v[94:97], v[20:23], v[4:7]
	ds_read_b128 v[94:97], v70 offset:8576
	s_waitcnt lgkmcnt(0)
	v_mfma_f32_16x16x32_bf16 v[4:7], v[94:97], v[16:19], v[4:7]
	ds_read_b128 v[94:97], v70 offset:8640
	s_waitcnt lgkmcnt(0)
	v_mfma_f32_16x16x32_bf16 v[4:7], v[94:97], v[12:15], v[4:7]
	v_mfma_f32_16x16x32_bf16 v[94:97], v[8:11], v[32:35], 0
	s_nop 7
	ds_write2_b32 v73, v94, v98 offset1:16
	ds_write2_b32 v73, v95, v99 offset0:132 offset1:148
	ds_write2_b32 v74, v96, v100 offset0:8 offset1:24
	ds_write2_b32 v74, v97, v101 offset0:140 offset1:156
	v_mfma_f32_16x16x32_bf16 v[94:97], v[8:11], v[40:43], 0
	v_mfma_f32_16x16x32_bf16 v[98:101], v[8:11], v[36:39], 0
	s_nop 7
	ds_write2_b32 v73, v94, v98 offset0:32 offset1:48
	ds_write2_b32 v73, v95, v99 offset0:164 offset1:180
	ds_write2_b32 v74, v96, v100 offset0:40 offset1:56
	ds_write2_b32 v74, v97, v101 offset0:172 offset1:188
	v_mfma_f32_16x16x32_bf16 v[94:97], v[8:11], v[48:51], 0
	v_mfma_f32_16x16x32_bf16 v[98:101], v[8:11], v[44:47], 0
	s_nop 7
	ds_write2_b32 v73, v94, v98 offset0:64 offset1:80
	ds_write2_b32 v73, v95, v99 offset0:196 offset1:212
	ds_write2_b32 v74, v96, v100 offset0:72 offset1:88
	ds_write2_b32 v74, v97, v101 offset0:204 offset1:220
	v_mfma_f32_16x16x32_bf16 v[94:97], v[8:11], v[56:59], 0
	v_mfma_f32_16x16x32_bf16 v[8:11], v[8:11], v[52:55], 0
	s_nop 7
	ds_write2_b32 v73, v94, v8 offset0:96 offset1:112
	ds_write2_b32 v73, v95, v9 offset0:228 offset1:244
	ds_write2_b32 v74, v96, v10 offset0:104 offset1:120
	ds_write2_b32 v74, v97, v11 offset0:236 offset1:252
	s_waitcnt vmcnt(0) lgkmcnt(0)
	ds_read2st64_b32 v[8:9], v75 offset1:1
	ds_read2_b32 v[140:141], v75 offset0:132 offset1:196
	ds_read2st64_b32 v[142:143], v71 offset0:4 offset1:5
	ds_read2st64_b32 v[144:145], v78 offset0:6 offset1:7
	ds_read2st64_b32 v[146:147], v79 offset0:8 offset1:9
	ds_read2st64_b32 v[148:149], v82 offset0:10 offset1:11
	ds_read2st64_b32 v[150:151], v83 offset0:12 offset1:13
	ds_read2st64_b32 v[152:153], v84 offset0:14 offset1:15
	ds_read2st64_b32 v[154:155], v85 offset0:16 offset1:17
	ds_read2st64_b32 v[156:157], v86 offset0:18 offset1:19
	ds_read2st64_b32 v[158:159], v87 offset0:20 offset1:21
	ds_read2st64_b32 v[160:161], v88 offset0:22 offset1:23
	ds_read2st64_b32 v[162:163], v89 offset0:24 offset1:25
	ds_read2st64_b32 v[164:165], v91 offset0:26 offset1:27
	ds_read2st64_b32 v[166:167], v92 offset0:28 offset1:29
	ds_read2st64_b32 v[168:169], v93 offset0:30 offset1:31
	v_mov_b32_e32 v186, v102
	v_mov_b32_e32 v187, v103
	v_mfma_f32_16x16x32_bf16 v[32:35], v[60:63], v[32:35], 0
	s_waitcnt lgkmcnt(0)
	v_pk_fma_f32 v[184:185], v[66:67], v[186:187], v[8:9] op_sel:[1,1,0] op_sel_hi:[1,0,1] neg_lo:[1,0,0]
	v_pk_fma_f32 v[188:189], v[66:67], v[186:187], v[184:185] op_sel_hi:[0,1,1]
	v_cvt_pk_bf16_f32 v190, v188, v189
	ds_write_b16 v72, v190 offset:8448
	ds_write_b16_d16_hi v72, v190 offset:8576
	v_pk_fma_f32 v[184:185], v[66:67], v[188:189], v[140:141] op_sel:[1,1,0] op_sel_hi:[1,0,1] neg_lo:[1,0,0]
	v_pk_fma_f32 v[186:187], v[66:67], v[188:189], v[184:185] op_sel_hi:[0,1,1]
	v_cvt_pk_bf16_f32 v190, v186, v187
	ds_write_b16 v72, v190 offset:8720
	ds_write_b16_d16_hi v72, v190 offset:8848
	v_pk_fma_f32 v[184:185], v[66:67], v[186:187], v[142:143] op_sel:[1,1,0] op_sel_hi:[1,0,1] neg_lo:[1,0,0]
	v_pk_fma_f32 v[188:189], v[66:67], v[186:187], v[184:185] op_sel_hi:[0,1,1]
	v_cvt_pk_bf16_f32 v190, v188, v189
	ds_write_b16 v72, v190 offset:8992
	ds_write_b16_d16_hi v72, v190 offset:9120
	v_pk_fma_f32 v[184:185], v[66:67], v[188:189], v[144:145] op_sel:[1,1,0] op_sel_hi:[1,0,1] neg_lo:[1,0,0]
	v_pk_fma_f32 v[186:187], v[66:67], v[188:189], v[184:185] op_sel_hi:[0,1,1]
	v_cvt_pk_bf16_f32 v190, v186, v187
	ds_write_b16 v72, v190 offset:9264
	ds_write_b16_d16_hi v72, v190 offset:9392
	v_pk_fma_f32 v[184:185], v[66:67], v[186:187], v[146:147] op_sel:[1,1,0] op_sel_hi:[1,0,1] neg_lo:[1,0,0]
	v_pk_fma_f32 v[188:189], v[66:67], v[186:187], v[184:185] op_sel_hi:[0,1,1]
	v_cvt_pk_bf16_f32 v190, v188, v189
	ds_write_b16 v72, v190 offset:9536
	ds_write_b16_d16_hi v72, v190 offset:9664
	v_pk_fma_f32 v[184:185], v[66:67], v[188:189], v[148:149] op_sel:[1,1,0] op_sel_hi:[1,0,1] neg_lo:[1,0,0]
	v_pk_fma_f32 v[186:187], v[66:67], v[188:189], v[184:185] op_sel_hi:[0,1,1]
	v_cvt_pk_bf16_f32 v190, v186, v187
	ds_write_b16 v72, v190 offset:9808
	ds_write_b16_d16_hi v72, v190 offset:9936
	v_pk_fma_f32 v[184:185], v[66:67], v[186:187], v[150:151] op_sel:[1,1,0] op_sel_hi:[1,0,1] neg_lo:[1,0,0]
	v_pk_fma_f32 v[188:189], v[66:67], v[186:187], v[184:185] op_sel_hi:[0,1,1]
	v_cvt_pk_bf16_f32 v190, v188, v189
	ds_write_b16 v72, v190 offset:10080
	ds_write_b16_d16_hi v72, v190 offset:10208
	v_pk_fma_f32 v[184:185], v[66:67], v[188:189], v[152:153] op_sel:[1,1,0] op_sel_hi:[1,0,1] neg_lo:[1,0,0]
	v_pk_fma_f32 v[186:187], v[66:67], v[188:189], v[184:185] op_sel_hi:[0,1,1]
	v_cvt_pk_bf16_f32 v190, v186, v187
	ds_write_b16 v72, v190 offset:10352
	ds_write_b16_d16_hi v72, v190 offset:10480
	v_pk_fma_f32 v[184:185], v[66:67], v[186:187], v[154:155] op_sel:[1,1,0] op_sel_hi:[1,0,1] neg_lo:[1,0,0]
	v_pk_fma_f32 v[188:189], v[66:67], v[186:187], v[184:185] op_sel_hi:[0,1,1]
	v_cvt_pk_bf16_f32 v190, v188, v189
	ds_write_b16 v72, v190 offset:10624
	ds_write_b16_d16_hi v72, v190 offset:10752
	v_pk_fma_f32 v[184:185], v[66:67], v[188:189], v[156:157] op_sel:[1,1,0] op_sel_hi:[1,0,1] neg_lo:[1,0,0]
	v_pk_fma_f32 v[186:187], v[66:67], v[188:189], v[184:185] op_sel_hi:[0,1,1]
	v_cvt_pk_bf16_f32 v190, v186, v187
	ds_write_b16 v72, v190 offset:10896
	ds_write_b16_d16_hi v72, v190 offset:11024
	v_pk_fma_f32 v[184:185], v[66:67], v[186:187], v[158:159] op_sel:[1,1,0] op_sel_hi:[1,0,1] neg_lo:[1,0,0]
	v_pk_fma_f32 v[188:189], v[66:67], v[186:187], v[184:185] op_sel_hi:[0,1,1]
	v_cvt_pk_bf16_f32 v190, v188, v189
	ds_write_b16 v72, v190 offset:11168
	ds_write_b16_d16_hi v72, v190 offset:11296
	v_pk_fma_f32 v[184:185], v[66:67], v[188:189], v[160:161] op_sel:[1,1,0] op_sel_hi:[1,0,1] neg_lo:[1,0,0]
	v_pk_fma_f32 v[186:187], v[66:67], v[188:189], v[184:185] op_sel_hi:[0,1,1]
	v_cvt_pk_bf16_f32 v190, v186, v187
	ds_write_b16 v72, v190 offset:11440
	ds_write_b16_d16_hi v72, v190 offset:11568
	v_pk_fma_f32 v[184:185], v[66:67], v[186:187], v[162:163] op_sel:[1,1,0] op_sel_hi:[1,0,1] neg_lo:[1,0,0]
	v_pk_fma_f32 v[188:189], v[66:67], v[186:187], v[184:185] op_sel_hi:[0,1,1]
	v_cvt_pk_bf16_f32 v190, v188, v189
	ds_write_b16 v72, v190 offset:11712
	ds_write_b16_d16_hi v72, v190 offset:11840
	v_pk_fma_f32 v[184:185], v[66:67], v[188:189], v[164:165] op_sel:[1,1,0] op_sel_hi:[1,0,1] neg_lo:[1,0,0]
	v_pk_fma_f32 v[186:187], v[66:67], v[188:189], v[184:185] op_sel_hi:[0,1,1]
	v_cvt_pk_bf16_f32 v190, v186, v187
	ds_write_b16 v72, v190 offset:11984
	ds_write_b16_d16_hi v72, v190 offset:12112
	v_pk_fma_f32 v[184:185], v[66:67], v[186:187], v[166:167] op_sel:[1,1,0] op_sel_hi:[1,0,1] neg_lo:[1,0,0]
	v_pk_fma_f32 v[188:189], v[66:67], v[186:187], v[184:185] op_sel_hi:[0,1,1]
	v_cvt_pk_bf16_f32 v190, v188, v189
	ds_write_b16 v72, v190 offset:12256
	ds_write_b16_d16_hi v72, v190 offset:12384
	v_pk_fma_f32 v[184:185], v[66:67], v[188:189], v[168:169] op_sel:[1,1,0] op_sel_hi:[1,0,1] neg_lo:[1,0,0]
	v_pk_fma_f32 v[186:187], v[66:67], v[188:189], v[184:185] op_sel_hi:[0,1,1]
	v_mov_b32_e32 v98, v186
	v_mov_b32_e32 v99, v187
	v_cvt_pk_bf16_f32 v190, v186, v187
	ds_write_b16 v72, v190 offset:12528
	ds_write_b16_d16_hi v72, v190 offset:12656
	s_waitcnt vmcnt(0) lgkmcnt(0)
	ds_read_b128 v[8:11], v70 offset:8448
	ds_read_b128 v[94:97], v70 offset:8512
	s_waitcnt lgkmcnt(1)
	v_mfma_f32_16x16x32_bf16 v[8:11], v[8:11], v[24:27], 0
	s_waitcnt lgkmcnt(0)
	v_mfma_f32_16x16x32_bf16 v[8:11], v[94:97], v[20:23], v[8:11]
	ds_read_b128 v[94:97], v70 offset:8576
	s_waitcnt lgkmcnt(0)
	v_mfma_f32_16x16x32_bf16 v[8:11], v[94:97], v[16:19], v[8:11]
	ds_read_b128 v[94:97], v70 offset:8640
	ds_write2_b32 v73, v32, v28 offset1:16
	ds_write2_b32 v73, v33, v29 offset0:132 offset1:148
	ds_write2_b32 v74, v34, v30 offset0:8 offset1:24
	ds_write2_b32 v74, v35, v31 offset0:140 offset1:156
	v_mfma_f32_16x16x32_bf16 v[28:31], v[60:63], v[40:43], 0
	v_mov_b32_e32 v40, 0
	v_mov_b32_e32 v41, 0
	v_mov_b32_e32 v42, 0
	v_mfma_f32_16x16x32_bf16 v[32:35], v[60:63], v[36:39], 0
	s_nop 7
	ds_write2_b32 v73, v28, v32 offset0:32 offset1:48
	ds_write2_b32 v73, v29, v33 offset0:164 offset1:180
	ds_write2_b32 v74, v30, v34 offset0:40 offset1:56
	ds_write2_b32 v74, v31, v35 offset0:172 offset1:188
	v_mfma_f32_16x16x32_bf16 v[28:31], v[60:63], v[48:51], 0
	v_mov_b32_e32 v36, 0
	v_mov_b32_e32 v43, 0
	v_mfma_f32_16x16x32_bf16 v[32:35], v[60:63], v[44:47], 0
	s_nop 7
	ds_write2_b32 v73, v28, v32 offset0:64 offset1:80
	ds_write2_b32 v73, v29, v33 offset0:196 offset1:212
	ds_write2_b32 v74, v30, v34 offset0:72 offset1:88
	ds_write2_b32 v74, v31, v35 offset0:204 offset1:220
	v_mfma_f32_16x16x32_bf16 v[28:31], v[60:63], v[56:59], 0
	v_mfma_f32_16x16x32_bf16 v[32:35], v[60:63], v[52:55], 0
	s_nop 7
	ds_write2_b32 v73, v28, v32 offset0:96 offset1:112
	ds_write2_b32 v73, v29, v33 offset0:228 offset1:244
	ds_write2_b32 v74, v30, v34 offset0:104 offset1:120
	ds_write2_b32 v74, v31, v35 offset0:236 offset1:252
	s_waitcnt vmcnt(0) lgkmcnt(0)
	ds_read2st64_b32 v[28:29], v75 offset1:1
	ds_read2_b32 v[140:141], v75 offset0:132 offset1:196
	ds_read2st64_b32 v[142:143], v71 offset0:4 offset1:5
	ds_read2st64_b32 v[144:145], v78 offset0:6 offset1:7
	ds_read2st64_b32 v[146:147], v79 offset0:8 offset1:9
	ds_read2st64_b32 v[148:149], v82 offset0:10 offset1:11
	ds_read2st64_b32 v[150:151], v83 offset0:12 offset1:13
	ds_read2st64_b32 v[152:153], v84 offset0:14 offset1:15
	ds_read2st64_b32 v[154:155], v85 offset0:16 offset1:17
	ds_read2st64_b32 v[156:157], v86 offset0:18 offset1:19
	ds_read2st64_b32 v[158:159], v87 offset0:20 offset1:21
	ds_read2st64_b32 v[160:161], v88 offset0:22 offset1:23
	ds_read2st64_b32 v[162:163], v89 offset0:24 offset1:25
	ds_read2st64_b32 v[164:165], v91 offset0:26 offset1:27
	ds_read2st64_b32 v[166:167], v92 offset0:28 offset1:29
	ds_read2st64_b32 v[168:169], v93 offset0:30 offset1:31
	v_mov_b32_e32 v186, v98
	v_mov_b32_e32 v187, v99
	s_waitcnt lgkmcnt(0)
	v_mfma_f32_16x16x32_bf16 v[8:11], v[94:97], v[12:15], v[8:11]
	v_pk_fma_f32 v[184:185], v[66:67], v[186:187], v[28:29] op_sel:[1,1,0] op_sel_hi:[1,0,1] neg_lo:[1,0,0]
	v_pk_fma_f32 v[188:189], v[66:67], v[186:187], v[184:185] op_sel_hi:[0,1,1]
	v_cvt_pk_bf16_f32 v190, v188, v189
	ds_write_b16 v72, v190 offset:8448
	ds_write_b16_d16_hi v72, v190 offset:8576
	v_pk_fma_f32 v[184:185], v[66:67], v[188:189], v[140:141] op_sel:[1,1,0] op_sel_hi:[1,0,1] neg_lo:[1,0,0]
	v_pk_fma_f32 v[186:187], v[66:67], v[188:189], v[184:185] op_sel_hi:[0,1,1]
	v_cvt_pk_bf16_f32 v190, v186, v187
	ds_write_b16 v72, v190 offset:8720
	ds_write_b16_d16_hi v72, v190 offset:8848
	v_pk_fma_f32 v[184:185], v[66:67], v[186:187], v[142:143] op_sel:[1,1,0] op_sel_hi:[1,0,1] neg_lo:[1,0,0]
	v_pk_fma_f32 v[188:189], v[66:67], v[186:187], v[184:185] op_sel_hi:[0,1,1]
	v_cvt_pk_bf16_f32 v190, v188, v189
	ds_write_b16 v72, v190 offset:8992
	ds_write_b16_d16_hi v72, v190 offset:9120
	v_pk_fma_f32 v[184:185], v[66:67], v[188:189], v[144:145] op_sel:[1,1,0] op_sel_hi:[1,0,1] neg_lo:[1,0,0]
	v_pk_fma_f32 v[186:187], v[66:67], v[188:189], v[184:185] op_sel_hi:[0,1,1]
	v_cvt_pk_bf16_f32 v190, v186, v187
	ds_write_b16 v72, v190 offset:9264
	ds_write_b16_d16_hi v72, v190 offset:9392
	v_pk_fma_f32 v[184:185], v[66:67], v[186:187], v[146:147] op_sel:[1,1,0] op_sel_hi:[1,0,1] neg_lo:[1,0,0]
	v_pk_fma_f32 v[188:189], v[66:67], v[186:187], v[184:185] op_sel_hi:[0,1,1]
	v_cvt_pk_bf16_f32 v190, v188, v189
	ds_write_b16 v72, v190 offset:9536
	ds_write_b16_d16_hi v72, v190 offset:9664
	v_pk_fma_f32 v[184:185], v[66:67], v[188:189], v[148:149] op_sel:[1,1,0] op_sel_hi:[1,0,1] neg_lo:[1,0,0]
	v_pk_fma_f32 v[186:187], v[66:67], v[188:189], v[184:185] op_sel_hi:[0,1,1]
	v_cvt_pk_bf16_f32 v190, v186, v187
	ds_write_b16 v72, v190 offset:9808
	ds_write_b16_d16_hi v72, v190 offset:9936
	v_pk_fma_f32 v[184:185], v[66:67], v[186:187], v[150:151] op_sel:[1,1,0] op_sel_hi:[1,0,1] neg_lo:[1,0,0]
	v_pk_fma_f32 v[188:189], v[66:67], v[186:187], v[184:185] op_sel_hi:[0,1,1]
	v_cvt_pk_bf16_f32 v190, v188, v189
	ds_write_b16 v72, v190 offset:10080
	ds_write_b16_d16_hi v72, v190 offset:10208
	v_pk_fma_f32 v[184:185], v[66:67], v[188:189], v[152:153] op_sel:[1,1,0] op_sel_hi:[1,0,1] neg_lo:[1,0,0]
	v_pk_fma_f32 v[186:187], v[66:67], v[188:189], v[184:185] op_sel_hi:[0,1,1]
	v_cvt_pk_bf16_f32 v190, v186, v187
	ds_write_b16 v72, v190 offset:10352
	ds_write_b16_d16_hi v72, v190 offset:10480
	v_pk_fma_f32 v[184:185], v[66:67], v[186:187], v[154:155] op_sel:[1,1,0] op_sel_hi:[1,0,1] neg_lo:[1,0,0]
	v_pk_fma_f32 v[188:189], v[66:67], v[186:187], v[184:185] op_sel_hi:[0,1,1]
	v_cvt_pk_bf16_f32 v190, v188, v189
	ds_write_b16 v72, v190 offset:10624
	ds_write_b16_d16_hi v72, v190 offset:10752
	v_pk_fma_f32 v[184:185], v[66:67], v[188:189], v[156:157] op_sel:[1,1,0] op_sel_hi:[1,0,1] neg_lo:[1,0,0]
	v_pk_fma_f32 v[186:187], v[66:67], v[188:189], v[184:185] op_sel_hi:[0,1,1]
	v_cvt_pk_bf16_f32 v190, v186, v187
	ds_write_b16 v72, v190 offset:10896
	ds_write_b16_d16_hi v72, v190 offset:11024
	v_pk_fma_f32 v[184:185], v[66:67], v[186:187], v[158:159] op_sel:[1,1,0] op_sel_hi:[1,0,1] neg_lo:[1,0,0]
	v_pk_fma_f32 v[188:189], v[66:67], v[186:187], v[184:185] op_sel_hi:[0,1,1]
	v_cvt_pk_bf16_f32 v190, v188, v189
	ds_write_b16 v72, v190 offset:11168
	ds_write_b16_d16_hi v72, v190 offset:11296
	v_pk_fma_f32 v[184:185], v[66:67], v[188:189], v[160:161] op_sel:[1,1,0] op_sel_hi:[1,0,1] neg_lo:[1,0,0]
	v_pk_fma_f32 v[186:187], v[66:67], v[188:189], v[184:185] op_sel_hi:[0,1,1]
	v_cvt_pk_bf16_f32 v190, v186, v187
	ds_write_b16 v72, v190 offset:11440
	ds_write_b16_d16_hi v72, v190 offset:11568
	v_pk_fma_f32 v[184:185], v[66:67], v[186:187], v[162:163] op_sel:[1,1,0] op_sel_hi:[1,0,1] neg_lo:[1,0,0]
	v_pk_fma_f32 v[188:189], v[66:67], v[186:187], v[184:185] op_sel_hi:[0,1,1]
	v_cvt_pk_bf16_f32 v190, v188, v189
	ds_write_b16 v72, v190 offset:11712
	ds_write_b16_d16_hi v72, v190 offset:11840
	v_pk_fma_f32 v[184:185], v[66:67], v[188:189], v[164:165] op_sel:[1,1,0] op_sel_hi:[1,0,1] neg_lo:[1,0,0]
	v_pk_fma_f32 v[186:187], v[66:67], v[188:189], v[184:185] op_sel_hi:[0,1,1]
	v_cvt_pk_bf16_f32 v190, v186, v187
	ds_write_b16 v72, v190 offset:11984
	ds_write_b16_d16_hi v72, v190 offset:12112
	v_pk_fma_f32 v[184:185], v[66:67], v[186:187], v[166:167] op_sel:[1,1,0] op_sel_hi:[1,0,1] neg_lo:[1,0,0]
	v_pk_fma_f32 v[188:189], v[66:67], v[186:187], v[184:185] op_sel_hi:[0,1,1]
	v_cvt_pk_bf16_f32 v190, v188, v189
	ds_write_b16 v72, v190 offset:12256
	ds_write_b16_d16_hi v72, v190 offset:12384
	v_pk_fma_f32 v[184:185], v[66:67], v[188:189], v[168:169] op_sel:[1,1,0] op_sel_hi:[1,0,1] neg_lo:[1,0,0]
	v_pk_fma_f32 v[186:187], v[66:67], v[188:189], v[184:185] op_sel_hi:[0,1,1]
	v_mov_b32_e32 v28, v186
	v_mov_b32_e32 v29, v187
	v_cvt_pk_bf16_f32 v190, v186, v187
	ds_write_b16 v72, v190 offset:12528
	ds_write_b16_d16_hi v72, v190 offset:12656
	s_waitcnt vmcnt(0) lgkmcnt(0)
	ds_read_b128 v[28:31], v70 offset:8448
	s_waitcnt lgkmcnt(0)
	v_mfma_f32_16x16x32_bf16 v[24:27], v[28:31], v[24:27], 0
	ds_read_b128 v[28:31], v70 offset:8512
	s_add_u32 s0, s0, s1
	s_addc_u32 s1, s2, 0
	s_waitcnt lgkmcnt(0)
	v_mfma_f32_16x16x32_bf16 v[20:23], v[28:31], v[20:23], v[24:27]
	s_nop 2
	ds_read_b128 v[24:27], v70 offset:8576
	s_lshl_b64 s[0:1], s[0:1], 14
	s_waitcnt lgkmcnt(0)
	v_mfma_f32_16x16x32_bf16 v[16:19], v[24:27], v[16:19], v[20:23]
	s_nop 2
	ds_read_b128 v[20:23], v70 offset:8640
	s_waitcnt lgkmcnt(0)
	v_mfma_f32_16x16x32_bf16 v[12:15], v[20:23], v[12:15], v[16:19]
	s_nop 2
	v_lshl_add_u64 v[16:17], v[64:65], 0, s[0:1]
	v_mov_b32_e32 v20, v207
	global_load_dwordx2 v[84:85], v[16:17], off
	v_add_u32_e32 v16, s90, v77
	v_and_b32_e32 v91, 63, v20
	v_or_b32_e32 v16, v91, v16
	v_ashrrev_i32_e32 v17, 31, v16
	v_lshl_add_u64 v[16:17], v[16:17], 3, s[60:61]
	global_load_dwordx2 v[82:83], v[16:17], off
	v_add_u32_e32 v16, s91, v76
	v_ashrrev_i32_e32 v17, 31, v16
	v_and_b32_e32 v92, 15, v20
	v_lshlrev_b64 v[16:17], 12, v[16:17]
	v_lshl_add_u64 v[18:19], s[62:63], 0, v[16:17]
	v_lshlrev_b32_e32 v21, 4, v92
	v_and_b32_e32 v128, 48, v20
	v_cmp_gt_u32_e64 s[42:43], 32, v91
	v_lshl_add_u64 v[18:19], v[18:19], 0, v[128:129]
	v_lshlrev_b32_e32 v128, 1, v21
	s_and_saveexec_b64 s[0:1], s[42:43]
	s_cbranch_execz .LBB0_1789
	v_lshl_add_u64 v[22:23], v[18:19], 0, v[128:129]
	global_load_dwordx4 v[40:43], v[22:23], off

.LBB0_1811:
	s_or_b64 exec, exec, s[0:1]
	s_waitcnt vmcnt(0) lgkmcnt(0)
	v_mfma_f32_16x16x32_bf16 v[94:97], v[16:19], v[40:43], 0
	v_mul_u32_u24_e32 v86, 0x210, v93
	v_lshlrev_b32_e32 v87, 2, v92
	v_lshlrev_b32_e32 v86, 2, v86
	v_mfma_f32_16x16x32_bf16 v[98:101], v[16:19], v[36:39], 0
	v_add3_u32 v88, v81, v87, v86
	v_add_u32_e32 v89, 0x400, v88
	v_mul_u32_u24_e32 v103, 0x110, v92
	s_nop 4
	ds_write2_b32 v88, v94, v98 offset1:16
	ds_write2_b32 v88, v95, v99 offset0:132 offset1:148
	ds_write2_b32 v89, v96, v100 offset0:8 offset1:24
	ds_write2_b32 v89, v97, v101 offset0:140 offset1:156
	v_mfma_f32_16x16x32_bf16 v[92:95], v[16:19], v[48:51], 0
	v_lshl_add_u32 v87, v91, 2, v81
	v_add3_u32 v81, v81, v128, v103
	v_pk_add_f32 v[0:1], v[0:1], 0 op_sel_hi:[1,0]
	v_mfma_f32_16x16x32_bf16 v[96:99], v[16:19], v[44:47], 0
	s_nop 7
	ds_write2_b32 v88, v92, v96 offset0:32 offset1:48
	ds_write2_b32 v88, v93, v97 offset0:164 offset1:180
	ds_write2_b32 v89, v94, v98 offset0:40 offset1:56
	ds_write2_b32 v89, v95, v99 offset0:172 offset1:188
	v_mfma_f32_16x16x32_bf16 v[92:95], v[16:19], v[56:59], 0
	v_readlane_b32 s68, v251, 41
	v_readlane_b32 s76, v251, 49
	v_readlane_b32 s77, v251, 50
	v_mfma_f32_16x16x32_bf16 v[96:99], v[16:19], v[52:55], 0
	s_nop 7
	ds_write2_b32 v88, v92, v96 offset0:64 offset1:80
	ds_write2_b32 v88, v93, v97 offset0:196 offset1:212
	ds_write2_b32 v89, v94, v98 offset0:72 offset1:88
	ds_write2_b32 v89, v95, v99 offset0:204 offset1:220
	v_mfma_f32_16x16x32_bf16 v[92:95], v[16:19], v[64:67], 0
	s_mov_b32 s10, 0x3f200000
	v_readlane_b32 s69, v251, 42
	v_readlane_b32 s70, v251, 43
	v_mfma_f32_16x16x32_bf16 v[16:19], v[16:19], v[60:63], 0
	s_nop 7
	ds_write2_b32 v88, v92, v16 offset0:96 offset1:112
	ds_write2_b32 v88, v93, v17 offset0:228 offset1:244
	ds_write2_b32 v89, v94, v18 offset0:104 offset1:120
	ds_write2_b32 v89, v95, v19 offset0:236 offset1:252
	v_lshlrev_b32_e32 v16, 1, v91
	v_add_u32_e32 v91, 0xf0, v87
	s_waitcnt vmcnt(0) lgkmcnt(0)
	v_sub_u32_e32 v86, v87, v16
	ds_read2st64_b32 v[16:17], v91 offset0:30 offset1:31
	v_add_u32_e32 v140, 0xe0, v87
	ds_read2st64_b32 v[142:143], v140 offset0:28 offset1:29
	v_add_u32_e32 v141, 0xd0, v87
	ds_read2st64_b32 v[144:145], v141 offset0:26 offset1:27
	v_add_u32_e32 v146, 0xc0, v87
	ds_read2st64_b32 v[148:149], v146 offset0:24 offset1:25
	v_add_u32_e32 v147, 0xb0, v87
	ds_read2st64_b32 v[150:151], v147 offset0:22 offset1:23
	v_add_u32_e32 v152, 0xa0, v87
	ds_read2st64_b32 v[154:155], v152 offset0:20 offset1:21
	v_add_u32_e32 v153, 0x90, v87
	ds_read2st64_b32 v[156:157], v153 offset0:18 offset1:19
	v_add_u32_e32 v158, 0x80, v87
	ds_read2st64_b32 v[160:161], v158 offset0:16 offset1:17
	v_add_u32_e32 v159, 0x70, v87
	ds_read2st64_b32 v[162:163], v159 offset0:14 offset1:15
	v_add_u32_e32 v164, 0x60, v87
	ds_read2st64_b32 v[166:167], v164 offset0:12 offset1:13
	v_add_u32_e32 v165, 0x50, v87
	ds_read2st64_b32 v[168:169], v165 offset0:10 offset1:11
	v_add_u32_e32 v170, 64, v87
	ds_read2st64_b32 v[172:173], v170 offset0:8 offset1:9
	v_add_u32_e32 v171, 48, v87
	ds_read2st64_b32 v[174:175], v171 offset0:6 offset1:7
	v_add_u32_e32 v176, 32, v87
	ds_read2st64_b32 v[178:179], v176 offset0:4 offset1:5
	ds_read2_b32 v[180:181], v87 offset0:132 offset1:196
	ds_read2st64_b32 v[182:183], v87 offset1:1
	v_mov_b32_e32 v186, v84
	v_mov_b32_e32 v187, v85
	v_mfma_f32_16x16x32_bf16 v[108:111], v[72:75], v[36:39], 0
	v_readlane_b32 s71, v251, 44
	s_waitcnt lgkmcnt(0)
	v_pk_fma_f32 v[184:185], v[82:83], v[186:187], v[16:17] op_sel:[1,1,0] op_sel_hi:[1,0,1] neg_lo:[1,0,0]
	v_pk_fma_f32 v[188:189], v[82:83], v[186:187], v[184:185] op_sel_hi:[0,1,1]
	v_cvt_pk_bf16_f32 v190, v188, v189
	ds_write_b16 v86, v190 offset:12528
	v_add_u32_e32 v84, 0xe0, v87
	ds_write_b16_d16_hi v86, v190 offset:12656
	v_readlane_b32 s72, v251, 45
	v_readlane_b32 s73, v251, 46
	v_pk_fma_f32 v[184:185], v[82:83], v[188:189], v[142:143] op_sel:[1,1,0] op_sel_hi:[1,0,1] neg_lo:[1,0,0]
	v_pk_fma_f32 v[186:187], v[82:83], v[188:189], v[184:185] op_sel_hi:[0,1,1]
	v_cvt_pk_bf16_f32 v190, v186, v187
	ds_write_b16 v86, v190 offset:12256
	v_add_u32_e32 v85, 0xd0, v87
	ds_write_b16_d16_hi v86, v190 offset:12384
	v_readlane_b32 s74, v251, 47
	v_readlane_b32 s75, v251, 48
	v_pk_fma_f32 v[184:185], v[82:83], v[186:187], v[144:145] op_sel:[1,1,0] op_sel_hi:[1,0,1] neg_lo:[1,0,0]
	v_pk_fma_f32 v[188:189], v[82:83], v[186:187], v[184:185] op_sel_hi:[0,1,1]
	v_cvt_pk_bf16_f32 v190, v188, v189
	ds_write_b16 v86, v190 offset:11984
	v_add_u32_e32 v92, 0xc0, v87
	ds_write_b16_d16_hi v86, v190 offset:12112
	v_readlane_b32 s78, v251, 51
	v_readlane_b32 s79, v251, 52
	v_pk_fma_f32 v[184:185], v[82:83], v[188:189], v[148:149] op_sel:[1,1,0] op_sel_hi:[1,0,1] neg_lo:[1,0,0]
	v_pk_fma_f32 v[186:187], v[82:83], v[188:189], v[184:185] op_sel_hi:[0,1,1]
	v_cvt_pk_bf16_f32 v190, v186, v187
	ds_write_b16 v86, v190 offset:11712
	v_add_u32_e32 v93, 0xb0, v87
	ds_write_b16_d16_hi v86, v190 offset:11840
	v_readlane_b32 s80, v251, 53
	v_readlane_b32 s81, v251, 54
	v_pk_fma_f32 v[184:185], v[82:83], v[186:187], v[150:151] op_sel:[1,1,0] op_sel_hi:[1,0,1] neg_lo:[1,0,0]
	v_pk_fma_f32 v[188:189], v[82:83], v[186:187], v[184:185] op_sel_hi:[0,1,1]
	v_cvt_pk_bf16_f32 v190, v188, v189
	ds_write_b16 v86, v190 offset:11440
	v_add_u32_e32 v94, 0xa0, v87
	ds_write_b16_d16_hi v86, v190 offset:11568
	v_readlane_b32 s82, v251, 55
	v_readlane_b32 s83, v251, 56
	v_pk_fma_f32 v[184:185], v[82:83], v[188:189], v[154:155] op_sel:[1,1,0] op_sel_hi:[1,0,1] neg_lo:[1,0,0]
	v_pk_fma_f32 v[186:187], v[82:83], v[188:189], v[184:185] op_sel_hi:[0,1,1]
	v_cvt_pk_bf16_f32 v190, v186, v187
	ds_write_b16 v86, v190 offset:11168
	v_add_u32_e32 v95, 0x90, v87
	ds_write_b16_d16_hi v86, v190 offset:11296
	v_pk_fma_f32 v[184:185], v[82:83], v[186:187], v[156:157] op_sel:[1,1,0] op_sel_hi:[1,0,1] neg_lo:[1,0,0]
	v_pk_fma_f32 v[188:189], v[82:83], v[186:187], v[184:185] op_sel_hi:[0,1,1]
	v_cvt_pk_bf16_f32 v190, v188, v189
	ds_write_b16 v86, v190 offset:10896
	v_add_u32_e32 v96, 0x80, v87
	ds_write_b16_d16_hi v86, v190 offset:11024
	v_pk_fma_f32 v[184:185], v[82:83], v[188:189], v[160:161] op_sel:[1,1,0] op_sel_hi:[1,0,1] neg_lo:[1,0,0]
	v_pk_fma_f32 v[186:187], v[82:83], v[188:189], v[184:185] op_sel_hi:[0,1,1]
	v_cvt_pk_bf16_f32 v190, v186, v187
	ds_write_b16 v86, v190 offset:10624
	v_add_u32_e32 v97, 0x70, v87
	ds_write_b16_d16_hi v86, v190 offset:10752
	v_pk_fma_f32 v[184:185], v[82:83], v[186:187], v[162:163] op_sel:[1,1,0] op_sel_hi:[1,0,1] neg_lo:[1,0,0]
	v_pk_fma_f32 v[188:189], v[82:83], v[186:187], v[184:185] op_sel_hi:[0,1,1]
	v_cvt_pk_bf16_f32 v190, v188, v189
	ds_write_b16 v86, v190 offset:10352
	v_add_u32_e32 v98, 0x60, v87
	ds_write_b16_d16_hi v86, v190 offset:10480
	v_pk_fma_f32 v[184:185], v[82:83], v[188:189], v[166:167] op_sel:[1,1,0] op_sel_hi:[1,0,1] neg_lo:[1,0,0]
	v_pk_fma_f32 v[186:187], v[82:83], v[188:189], v[184:185] op_sel_hi:[0,1,1]
	v_cvt_pk_bf16_f32 v190, v186, v187
	ds_write_b16 v86, v190 offset:10080
	v_add_u32_e32 v99, 0x50, v87
	ds_write_b16_d16_hi v86, v190 offset:10208
	v_pk_fma_f32 v[184:185], v[82:83], v[186:187], v[168:169] op_sel:[1,1,0] op_sel_hi:[1,0,1] neg_lo:[1,0,0]
	v_pk_fma_f32 v[188:189], v[82:83], v[186:187], v[184:185] op_sel_hi:[0,1,1]
	v_cvt_pk_bf16_f32 v190, v188, v189
	ds_write_b16 v86, v190 offset:9808
	v_add_u32_e32 v100, 64, v87
	ds_write_b16_d16_hi v86, v190 offset:9936
	v_pk_fma_f32 v[184:185], v[82:83], v[188:189], v[172:173] op_sel:[1,1,0] op_sel_hi:[1,0,1] neg_lo:[1,0,0]
	v_pk_fma_f32 v[186:187], v[82:83], v[188:189], v[184:185] op_sel_hi:[0,1,1]
	v_cvt_pk_bf16_f32 v190, v186, v187
	ds_write_b16 v86, v190 offset:9536
	v_add_u32_e32 v101, 48, v87
	ds_write_b16_d16_hi v86, v190 offset:9664
	v_pk_fma_f32 v[184:185], v[82:83], v[186:187], v[174:175] op_sel:[1,1,0] op_sel_hi:[1,0,1] neg_lo:[1,0,0]
	v_pk_fma_f32 v[188:189], v[82:83], v[186:187], v[184:185] op_sel_hi:[0,1,1]
	v_cvt_pk_bf16_f32 v190, v188, v189
	ds_write_b16 v86, v190 offset:9264
	v_add_u32_e32 v102, 32, v87
	ds_write_b16_d16_hi v86, v190 offset:9392
	v_pk_fma_f32 v[184:185], v[82:83], v[188:189], v[178:179] op_sel:[1,1,0] op_sel_hi:[1,0,1] neg_lo:[1,0,0]
	v_pk_fma_f32 v[186:187], v[82:83], v[188:189], v[184:185] op_sel_hi:[0,1,1]
	v_cvt_pk_bf16_f32 v190, v186, v187
	ds_write_b16 v86, v190 offset:8992
	ds_write_b16_d16_hi v86, v190 offset:9120
	v_pk_fma_f32 v[184:185], v[82:83], v[186:187], v[180:181] op_sel:[1,1,0] op_sel_hi:[1,0,1] neg_lo:[1,0,0]
	v_pk_fma_f32 v[188:189], v[82:83], v[186:187], v[184:185] op_sel_hi:[0,1,1]
	v_cvt_pk_bf16_f32 v190, v188, v189
	ds_write_b16 v86, v190 offset:8720
	ds_write_b16_d16_hi v86, v190 offset:8848
	v_pk_fma_f32 v[184:185], v[82:83], v[188:189], v[182:183] op_sel:[1,1,0] op_sel_hi:[1,0,1] neg_lo:[1,0,0]
	v_pk_fma_f32 v[186:187], v[82:83], v[188:189], v[184:185] op_sel_hi:[0,1,1]
	v_mov_b32_e32 v112, v186
	v_mov_b32_e32 v113, v187
	v_cvt_pk_bf16_f32 v190, v186, v187
	ds_write_b16 v86, v190 offset:8448
	ds_write_b16_d16_hi v86, v190 offset:8576
	s_waitcnt vmcnt(0) lgkmcnt(0)
	ds_read_b128 v[16:19], v81 offset:8448
	ds_read_b128 v[104:107], v81 offset:8512
	s_waitcnt lgkmcnt(1)
	v_mfma_f32_16x16x32_bf16 v[16:19], v[16:19], v[32:35], 0
	s_waitcnt lgkmcnt(0)
	v_mfma_f32_16x16x32_bf16 v[16:19], v[104:107], v[28:31], v[16:19]
	ds_read_b128 v[104:107], v81 offset:8576
	s_waitcnt lgkmcnt(0)
	v_mfma_f32_16x16x32_bf16 v[16:19], v[104:107], v[24:27], v[16:19]
	ds_read_b128 v[104:107], v81 offset:8640
	s_waitcnt lgkmcnt(0)
	v_mfma_f32_16x16x32_bf16 v[16:19], v[104:107], v[20:23], v[16:19]
	v_mfma_f32_16x16x32_bf16 v[104:107], v[72:75], v[40:43], 0
	s_nop 7
	ds_write2_b32 v88, v104, v108 offset1:16
	ds_write2_b32 v88, v105, v109 offset0:132 offset1:148
	ds_write2_b32 v89, v106, v110 offset0:8 offset1:24
	ds_write2_b32 v89, v107, v111 offset0:140 offset1:156
	v_mfma_f32_16x16x32_bf16 v[104:107], v[72:75], v[48:51], 0
	v_mfma_f32_16x16x32_bf16 v[108:111], v[72:75], v[44:47], 0
	s_nop 7
	ds_write2_b32 v88, v104, v108 offset0:32 offset1:48
	ds_write2_b32 v88, v105, v109 offset0:164 offset1:180
	ds_write2_b32 v89, v106, v110 offset0:40 offset1:56
	ds_write2_b32 v89, v107, v111 offset0:172 offset1:188
	v_mfma_f32_16x16x32_bf16 v[104:107], v[72:75], v[56:59], 0
	v_mfma_f32_16x16x32_bf16 v[108:111], v[72:75], v[52:55], 0
	s_nop 7
	ds_write2_b32 v88, v104, v108 offset0:64 offset1:80
	ds_write2_b32 v88, v105, v109 offset0:196 offset1:212
	ds_write2_b32 v89, v106, v110 offset0:72 offset1:88
	ds_write2_b32 v89, v107, v111 offset0:204 offset1:220
	v_mfma_f32_16x16x32_bf16 v[104:107], v[72:75], v[64:67], 0
	v_mfma_f32_16x16x32_bf16 v[72:75], v[72:75], v[60:63], 0
	s_nop 7
	ds_write2_b32 v88, v104, v72 offset0:96 offset1:112
	ds_write2_b32 v88, v105, v73 offset0:228 offset1:244
	ds_write2_b32 v89, v106, v74 offset0:104 offset1:120
	ds_write2_b32 v89, v107, v75 offset0:236 offset1:252
	s_waitcnt vmcnt(0) lgkmcnt(0)
	ds_read2st64_b32 v[72:73], v91 offset0:30 offset1:31
	ds_read2st64_b32 v[140:141], v84 offset0:28 offset1:29
	ds_read2st64_b32 v[142:143], v85 offset0:26 offset1:27
	ds_read2st64_b32 v[144:145], v92 offset0:24 offset1:25
	ds_read2st64_b32 v[146:147], v93 offset0:22 offset1:23
	ds_read2st64_b32 v[148:149], v94 offset0:20 offset1:21
	ds_read2st64_b32 v[150:151], v95 offset0:18 offset1:19
	ds_read2st64_b32 v[152:153], v96 offset0:16 offset1:17
	ds_read2st64_b32 v[154:155], v97 offset0:14 offset1:15
	ds_read2st64_b32 v[156:157], v98 offset0:12 offset1:13
	ds_read2st64_b32 v[158:159], v99 offset0:10 offset1:11
	ds_read2st64_b32 v[160:161], v100 offset0:8 offset1:9
	ds_read2st64_b32 v[162:163], v101 offset0:6 offset1:7
	ds_read2st64_b32 v[164:165], v102 offset0:4 offset1:5
	ds_read2_b32 v[166:167], v87 offset0:132 offset1:196
	ds_read2st64_b32 v[168:169], v87 offset1:1
	v_mov_b32_e32 v186, v112
	v_mov_b32_e32 v187, v113
	v_mfma_f32_16x16x32_bf16 v[108:111], v[76:79], v[36:39], 0
	s_waitcnt lgkmcnt(0)
	v_pk_fma_f32 v[184:185], v[82:83], v[186:187], v[72:73] op_sel:[1,1,0] op_sel_hi:[1,0,1] neg_lo:[1,0,0]
	v_pk_fma_f32 v[188:189], v[82:83], v[186:187], v[184:185] op_sel_hi:[0,1,1]
	v_cvt_pk_bf16_f32 v190, v188, v189
	ds_write_b16 v86, v190 offset:12528
	ds_write_b16_d16_hi v86, v190 offset:12656
	v_mfma_f32_16x16x32_bf16 v[36:39], v[68:71], v[36:39], 0
	v_pk_fma_f32 v[184:185], v[82:83], v[188:189], v[140:141] op_sel:[1,1,0] op_sel_hi:[1,0,1] neg_lo:[1,0,0]
	v_pk_fma_f32 v[186:187], v[82:83], v[188:189], v[184:185] op_sel_hi:[0,1,1]
	v_cvt_pk_bf16_f32 v190, v186, v187
	ds_write_b16 v86, v190 offset:12256
	ds_write_b16_d16_hi v86, v190 offset:12384
	v_pk_fma_f32 v[184:185], v[82:83], v[186:187], v[142:143] op_sel:[1,1,0] op_sel_hi:[1,0,1] neg_lo:[1,0,0]
	v_pk_fma_f32 v[188:189], v[82:83], v[186:187], v[184:185] op_sel_hi:[0,1,1]
	v_cvt_pk_bf16_f32 v190, v188, v189
	ds_write_b16 v86, v190 offset:11984
	ds_write_b16_d16_hi v86, v190 offset:12112
	v_pk_fma_f32 v[184:185], v[82:83], v[188:189], v[144:145] op_sel:[1,1,0] op_sel_hi:[1,0,1] neg_lo:[1,0,0]
	v_pk_fma_f32 v[186:187], v[82:83], v[188:189], v[184:185] op_sel_hi:[0,1,1]
	v_cvt_pk_bf16_f32 v190, v186, v187
	ds_write_b16 v86, v190 offset:11712
	ds_write_b16_d16_hi v86, v190 offset:11840
	v_pk_fma_f32 v[184:185], v[82:83], v[186:187], v[146:147] op_sel:[1,1,0] op_sel_hi:[1,0,1] neg_lo:[1,0,0]
	v_pk_fma_f32 v[188:189], v[82:83], v[186:187], v[184:185] op_sel_hi:[0,1,1]
	v_cvt_pk_bf16_f32 v190, v188, v189
	ds_write_b16 v86, v190 offset:11440
	ds_write_b16_d16_hi v86, v190 offset:11568
	v_pk_fma_f32 v[184:185], v[82:83], v[188:189], v[148:149] op_sel:[1,1,0] op_sel_hi:[1,0,1] neg_lo:[1,0,0]
	v_pk_fma_f32 v[186:187], v[82:83], v[188:189], v[184:185] op_sel_hi:[0,1,1]
	v_cvt_pk_bf16_f32 v190, v186, v187
	ds_write_b16 v86, v190 offset:11168
	ds_write_b16_d16_hi v86, v190 offset:11296
	v_pk_fma_f32 v[184:185], v[82:83], v[186:187], v[150:151] op_sel:[1,1,0] op_sel_hi:[1,0,1] neg_lo:[1,0,0]
	v_pk_fma_f32 v[188:189], v[82:83], v[186:187], v[184:185] op_sel_hi:[0,1,1]
	v_cvt_pk_bf16_f32 v190, v188, v189
	ds_write_b16 v86, v190 offset:10896
	ds_write_b16_d16_hi v86, v190 offset:11024
	v_pk_fma_f32 v[184:185], v[82:83], v[188:189], v[152:153] op_sel:[1,1,0] op_sel_hi:[1,0,1] neg_lo:[1,0,0]
	v_pk_fma_f32 v[186:187], v[82:83], v[188:189], v[184:185] op_sel_hi:[0,1,1]
	v_cvt_pk_bf16_f32 v190, v186, v187
	ds_write_b16 v86, v190 offset:10624
	ds_write_b16_d16_hi v86, v190 offset:10752
	v_pk_fma_f32 v[184:185], v[82:83], v[186:187], v[154:155] op_sel:[1,1,0] op_sel_hi:[1,0,1] neg_lo:[1,0,0]
	v_pk_fma_f32 v[188:189], v[82:83], v[186:187], v[184:185] op_sel_hi:[0,1,1]
	v_cvt_pk_bf16_f32 v190, v188, v189
	ds_write_b16 v86, v190 offset:10352
	ds_write_b16_d16_hi v86, v190 offset:10480
	v_pk_fma_f32 v[184:185], v[82:83], v[188:189], v[156:157] op_sel:[1,1,0] op_sel_hi:[1,0,1] neg_lo:[1,0,0]
	v_pk_fma_f32 v[186:187], v[82:83], v[188:189], v[184:185] op_sel_hi:[0,1,1]
	v_cvt_pk_bf16_f32 v190, v186, v187
	ds_write_b16 v86, v190 offset:10080
	ds_write_b16_d16_hi v86, v190 offset:10208
	v_pk_fma_f32 v[184:185], v[82:83], v[186:187], v[158:159] op_sel:[1,1,0] op_sel_hi:[1,0,1] neg_lo:[1,0,0]
	v_pk_fma_f32 v[188:189], v[82:83], v[186:187], v[184:185] op_sel_hi:[0,1,1]
	v_cvt_pk_bf16_f32 v190, v188, v189
	ds_write_b16 v86, v190 offset:9808
	ds_write_b16_d16_hi v86, v190 offset:9936
	v_pk_fma_f32 v[184:185], v[82:83], v[188:189], v[160:161] op_sel:[1,1,0] op_sel_hi:[1,0,1] neg_lo:[1,0,0]
	v_pk_fma_f32 v[186:187], v[82:83], v[188:189], v[184:185] op_sel_hi:[0,1,1]
	v_cvt_pk_bf16_f32 v190, v186, v187
	ds_write_b16 v86, v190 offset:9536
	ds_write_b16_d16_hi v86, v190 offset:9664
	v_pk_fma_f32 v[184:185], v[82:83], v[186:187], v[162:163] op_sel:[1,1,0] op_sel_hi:[1,0,1] neg_lo:[1,0,0]
	v_pk_fma_f32 v[188:189], v[82:83], v[186:187], v[184:185] op_sel_hi:[0,1,1]
	v_cvt_pk_bf16_f32 v190, v188, v189
	ds_write_b16 v86, v190 offset:9264
	ds_write_b16_d16_hi v86, v190 offset:9392
	v_pk_fma_f32 v[184:185], v[82:83], v[188:189], v[164:165] op_sel:[1,1,0] op_sel_hi:[1,0,1] neg_lo:[1,0,0]
	v_pk_fma_f32 v[186:187], v[82:83], v[188:189], v[184:185] op_sel_hi:[0,1,1]
	v_cvt_pk_bf16_f32 v190, v186, v187
	ds_write_b16 v86, v190 offset:8992
	ds_write_b16_d16_hi v86, v190 offset:9120
	v_pk_fma_f32 v[184:185], v[82:83], v[186:187], v[166:167] op_sel:[1,1,0] op_sel_hi:[1,0,1] neg_lo:[1,0,0]
	v_pk_fma_f32 v[188:189], v[82:83], v[186:187], v[184:185] op_sel_hi:[0,1,1]
	v_cvt_pk_bf16_f32 v190, v188, v189
	ds_write_b16 v86, v190 offset:8720
	ds_write_b16_d16_hi v86, v190 offset:8848
	v_pk_fma_f32 v[184:185], v[82:83], v[188:189], v[168:169] op_sel:[1,1,0] op_sel_hi:[1,0,1] neg_lo:[1,0,0]
	v_pk_fma_f32 v[186:187], v[82:83], v[188:189], v[184:185] op_sel_hi:[0,1,1]
	v_mov_b32_e32 v103, v186
	v_mov_b32_e32 v112, v187
	v_cvt_pk_bf16_f32 v190, v186, v187
	ds_write_b16 v86, v190 offset:8448
	ds_write_b16_d16_hi v86, v190 offset:8576
	s_waitcnt vmcnt(0) lgkmcnt(0)
	ds_read_b128 v[72:75], v81 offset:8448
	ds_read_b128 v[104:107], v81 offset:8512
	s_waitcnt lgkmcnt(1)
	v_mfma_f32_16x16x32_bf16 v[72:75], v[72:75], v[32:35], 0
	s_waitcnt lgkmcnt(0)
	v_mfma_f32_16x16x32_bf16 v[72:75], v[104:107], v[28:31], v[72:75]
	ds_read_b128 v[104:107], v81 offset:8576
	s_waitcnt lgkmcnt(0)
	v_mfma_f32_16x16x32_bf16 v[72:75], v[104:107], v[24:27], v[72:75]
	ds_read_b128 v[104:107], v81 offset:8640
	s_waitcnt lgkmcnt(0)
	v_mfma_f32_16x16x32_bf16 v[72:75], v[104:107], v[20:23], v[72:75]
	v_mfma_f32_16x16x32_bf16 v[104:107], v[76:79], v[40:43], 0
	s_nop 7
	ds_write2_b32 v88, v104, v108 offset1:16
	ds_write2_b32 v88, v105, v109 offset0:132 offset1:148
	ds_write2_b32 v89, v106, v110 offset0:8 offset1:24
	ds_write2_b32 v89, v107, v111 offset0:140 offset1:156
	v_mfma_f32_16x16x32_bf16 v[104:107], v[76:79], v[48:51], 0
	v_mfma_f32_16x16x32_bf16 v[108:111], v[76:79], v[44:47], 0
	s_nop 7
	ds_write2_b32 v88, v104, v108 offset0:32 offset1:48
	ds_write2_b32 v88, v105, v109 offset0:164 offset1:180
	ds_write2_b32 v89, v106, v110 offset0:40 offset1:56
	ds_write2_b32 v89, v107, v111 offset0:172 offset1:188
	v_mfma_f32_16x16x32_bf16 v[104:107], v[76:79], v[56:59], 0
	v_mfma_f32_16x16x32_bf16 v[108:111], v[76:79], v[52:55], 0
	s_nop 7
	ds_write2_b32 v88, v104, v108 offset0:64 offset1:80
	ds_write2_b32 v88, v105, v109 offset0:196 offset1:212
	ds_write2_b32 v89, v106, v110 offset0:72 offset1:88
	ds_write2_b32 v89, v107, v111 offset0:204 offset1:220
	v_mfma_f32_16x16x32_bf16 v[104:107], v[76:79], v[64:67], 0
	v_mfma_f32_16x16x32_bf16 v[76:79], v[76:79], v[60:63], 0
	s_nop 7
	ds_write2_b32 v88, v104, v76 offset0:96 offset1:112
	ds_write2_b32 v88, v105, v77 offset0:228 offset1:244
	ds_write2_b32 v89, v106, v78 offset0:104 offset1:120
	ds_write2_b32 v89, v107, v79 offset0:236 offset1:252
	s_waitcnt vmcnt(0) lgkmcnt(0)
	ds_read2st64_b32 v[76:77], v91 offset0:30 offset1:31
	ds_read2st64_b32 v[140:141], v84 offset0:28 offset1:29
	ds_read2st64_b32 v[142:143], v85 offset0:26 offset1:27
	ds_read2st64_b32 v[144:145], v92 offset0:24 offset1:25
	ds_read2st64_b32 v[146:147], v93 offset0:22 offset1:23
	ds_read2st64_b32 v[148:149], v94 offset0:20 offset1:21
	ds_read2st64_b32 v[150:151], v95 offset0:18 offset1:19
	ds_read2st64_b32 v[152:153], v96 offset0:16 offset1:17
	ds_read2st64_b32 v[154:155], v97 offset0:14 offset1:15
	ds_read2st64_b32 v[156:157], v98 offset0:12 offset1:13
	ds_read2st64_b32 v[158:159], v99 offset0:10 offset1:11
	ds_read2st64_b32 v[160:161], v100 offset0:8 offset1:9
	ds_read2st64_b32 v[162:163], v101 offset0:6 offset1:7
	ds_read2st64_b32 v[164:165], v102 offset0:4 offset1:5
	ds_read2_b32 v[166:167], v87 offset0:132 offset1:196
	ds_read2st64_b32 v[168:169], v87 offset1:1
	v_mov_b32_e32 v186, v103
	v_mov_b32_e32 v187, v112
	v_mfma_f32_16x16x32_bf16 v[40:43], v[68:71], v[40:43], 0
	s_waitcnt lgkmcnt(0)
	v_pk_fma_f32 v[184:185], v[82:83], v[186:187], v[76:77] op_sel:[1,1,0] op_sel_hi:[1,0,1] neg_lo:[1,0,0]
	v_pk_fma_f32 v[188:189], v[82:83], v[186:187], v[184:185] op_sel_hi:[0,1,1]
	v_cvt_pk_bf16_f32 v190, v188, v189
	ds_write_b16 v86, v190 offset:12528
	ds_write_b16_d16_hi v86, v190 offset:12656
	v_pk_fma_f32 v[184:185], v[82:83], v[188:189], v[140:141] op_sel:[1,1,0] op_sel_hi:[1,0,1] neg_lo:[1,0,0]
	v_pk_fma_f32 v[186:187], v[82:83], v[188:189], v[184:185] op_sel_hi:[0,1,1]
	v_cvt_pk_bf16_f32 v190, v186, v187
	ds_write_b16 v86, v190 offset:12256
	ds_write_b16_d16_hi v86, v190 offset:12384
	v_pk_fma_f32 v[184:185], v[82:83], v[186:187], v[142:143] op_sel:[1,1,0] op_sel_hi:[1,0,1] neg_lo:[1,0,0]
	v_pk_fma_f32 v[188:189], v[82:83], v[186:187], v[184:185] op_sel_hi:[0,1,1]
	v_cvt_pk_bf16_f32 v190, v188, v189
	ds_write_b16 v86, v190 offset:11984
	ds_write_b16_d16_hi v86, v190 offset:12112
	v_pk_fma_f32 v[184:185], v[82:83], v[188:189], v[144:145] op_sel:[1,1,0] op_sel_hi:[1,0,1] neg_lo:[1,0,0]
	v_pk_fma_f32 v[186:187], v[82:83], v[188:189], v[184:185] op_sel_hi:[0,1,1]
	v_cvt_pk_bf16_f32 v190, v186, v187
	ds_write_b16 v86, v190 offset:11712
	ds_write_b16_d16_hi v86, v190 offset:11840
	v_pk_fma_f32 v[184:185], v[82:83], v[186:187], v[146:147] op_sel:[1,1,0] op_sel_hi:[1,0,1] neg_lo:[1,0,0]
	v_pk_fma_f32 v[188:189], v[82:83], v[186:187], v[184:185] op_sel_hi:[0,1,1]
	v_cvt_pk_bf16_f32 v190, v188, v189
	ds_write_b16 v86, v190 offset:11440
	ds_write_b16_d16_hi v86, v190 offset:11568
	v_pk_fma_f32 v[184:185], v[82:83], v[188:189], v[148:149] op_sel:[1,1,0] op_sel_hi:[1,0,1] neg_lo:[1,0,0]
	v_pk_fma_f32 v[186:187], v[82:83], v[188:189], v[184:185] op_sel_hi:[0,1,1]
	v_cvt_pk_bf16_f32 v190, v186, v187
	ds_write_b16 v86, v190 offset:11168
	ds_write_b16_d16_hi v86, v190 offset:11296
	v_pk_fma_f32 v[184:185], v[82:83], v[186:187], v[150:151] op_sel:[1,1,0] op_sel_hi:[1,0,1] neg_lo:[1,0,0]
	v_pk_fma_f32 v[188:189], v[82:83], v[186:187], v[184:185] op_sel_hi:[0,1,1]
	v_cvt_pk_bf16_f32 v190, v188, v189
	ds_write_b16 v86, v190 offset:10896
	ds_write_b16_d16_hi v86, v190 offset:11024
	v_pk_fma_f32 v[184:185], v[82:83], v[188:189], v[152:153] op_sel:[1,1,0] op_sel_hi:[1,0,1] neg_lo:[1,0,0]
	v_pk_fma_f32 v[186:187], v[82:83], v[188:189], v[184:185] op_sel_hi:[0,1,1]
	v_cvt_pk_bf16_f32 v190, v186, v187
	ds_write_b16 v86, v190 offset:10624
	ds_write_b16_d16_hi v86, v190 offset:10752
	v_pk_fma_f32 v[184:185], v[82:83], v[186:187], v[154:155] op_sel:[1,1,0] op_sel_hi:[1,0,1] neg_lo:[1,0,0]
	v_pk_fma_f32 v[188:189], v[82:83], v[186:187], v[184:185] op_sel_hi:[0,1,1]
	v_cvt_pk_bf16_f32 v190, v188, v189
	ds_write_b16 v86, v190 offset:10352
	ds_write_b16_d16_hi v86, v190 offset:10480
	v_pk_fma_f32 v[184:185], v[82:83], v[188:189], v[156:157] op_sel:[1,1,0] op_sel_hi:[1,0,1] neg_lo:[1,0,0]
	v_pk_fma_f32 v[186:187], v[82:83], v[188:189], v[184:185] op_sel_hi:[0,1,1]
	v_cvt_pk_bf16_f32 v190, v186, v187
	ds_write_b16 v86, v190 offset:10080
	ds_write_b16_d16_hi v86, v190 offset:10208
	v_pk_fma_f32 v[184:185], v[82:83], v[186:187], v[158:159] op_sel:[1,1,0] op_sel_hi:[1,0,1] neg_lo:[1,0,0]
	v_pk_fma_f32 v[188:189], v[82:83], v[186:187], v[184:185] op_sel_hi:[0,1,1]
	v_cvt_pk_bf16_f32 v190, v188, v189
	ds_write_b16 v86, v190 offset:9808
	ds_write_b16_d16_hi v86, v190 offset:9936
	v_pk_fma_f32 v[184:185], v[82:83], v[188:189], v[160:161] op_sel:[1,1,0] op_sel_hi:[1,0,1] neg_lo:[1,0,0]
	v_pk_fma_f32 v[186:187], v[82:83], v[188:189], v[184:185] op_sel_hi:[0,1,1]
	v_cvt_pk_bf16_f32 v190, v186, v187
	ds_write_b16 v86, v190 offset:9536
	ds_write_b16_d16_hi v86, v190 offset:9664
	v_pk_fma_f32 v[184:185], v[82:83], v[186:187], v[162:163] op_sel:[1,1,0] op_sel_hi:[1,0,1] neg_lo:[1,0,0]
	v_pk_fma_f32 v[188:189], v[82:83], v[186:187], v[184:185] op_sel_hi:[0,1,1]
	v_cvt_pk_bf16_f32 v190, v188, v189
	ds_write_b16 v86, v190 offset:9264
	ds_write_b16_d16_hi v86, v190 offset:9392
	v_pk_fma_f32 v[184:185], v[82:83], v[188:189], v[164:165] op_sel:[1,1,0] op_sel_hi:[1,0,1] neg_lo:[1,0,0]
	v_pk_fma_f32 v[186:187], v[82:83], v[188:189], v[184:185] op_sel_hi:[0,1,1]
	v_cvt_pk_bf16_f32 v190, v186, v187
	ds_write_b16 v86, v190 offset:8992
	ds_write_b16_d16_hi v86, v190 offset:9120
	v_pk_fma_f32 v[184:185], v[82:83], v[186:187], v[166:167] op_sel:[1,1,0] op_sel_hi:[1,0,1] neg_lo:[1,0,0]
	v_pk_fma_f32 v[188:189], v[82:83], v[186:187], v[184:185] op_sel_hi:[0,1,1]
	v_cvt_pk_bf16_f32 v190, v188, v189
	ds_write_b16 v86, v190 offset:8720
	ds_write_b16_d16_hi v86, v190 offset:8848
	v_pk_fma_f32 v[184:185], v[82:83], v[188:189], v[168:169] op_sel:[1,1,0] op_sel_hi:[1,0,1] neg_lo:[1,0,0]
	v_pk_fma_f32 v[186:187], v[82:83], v[188:189], v[184:185] op_sel_hi:[0,1,1]
	v_mov_b32_e32 v103, v186
	v_mov_b32_e32 v108, v187
	v_cvt_pk_bf16_f32 v190, v186, v187
	ds_write_b16 v86, v190 offset:8448
	ds_write_b16_d16_hi v86, v190 offset:8576
	s_waitcnt vmcnt(0) lgkmcnt(0)
	ds_read_b128 v[76:79], v81 offset:8448
	ds_read_b128 v[104:107], v81 offset:8512
	s_waitcnt lgkmcnt(1)
	v_mfma_f32_16x16x32_bf16 v[76:79], v[76:79], v[32:35], 0
	s_waitcnt lgkmcnt(0)
	v_mfma_f32_16x16x32_bf16 v[76:79], v[104:107], v[28:31], v[76:79]
	ds_read_b128 v[104:107], v81 offset:8576
	s_waitcnt lgkmcnt(0)
	v_mfma_f32_16x16x32_bf16 v[76:79], v[104:107], v[24:27], v[76:79]
	ds_read_b128 v[104:107], v81 offset:8640
	ds_write2_b32 v88, v40, v36 offset1:16
	ds_write2_b32 v88, v41, v37 offset0:132 offset1:148
	ds_write2_b32 v89, v42, v38 offset0:8 offset1:24
	ds_write2_b32 v89, v43, v39 offset0:140 offset1:156
	v_mfma_f32_16x16x32_bf16 v[36:39], v[68:71], v[48:51], 0
	v_mfma_f32_16x16x32_bf16 v[40:43], v[68:71], v[44:47], 0
	s_nop 7
	ds_write2_b32 v88, v36, v40 offset0:32 offset1:48
	ds_write2_b32 v88, v37, v41 offset0:164 offset1:180
	ds_write2_b32 v89, v38, v42 offset0:40 offset1:56
	ds_write2_b32 v89, v39, v43 offset0:172 offset1:188
	v_mfma_f32_16x16x32_bf16 v[36:39], v[68:71], v[56:59], 0
	v_mfma_f32_16x16x32_bf16 v[40:43], v[68:71], v[52:55], 0
	s_nop 7
	ds_write2_b32 v88, v36, v40 offset0:64 offset1:80
	ds_write2_b32 v88, v37, v41 offset0:196 offset1:212
	ds_write2_b32 v89, v38, v42 offset0:72 offset1:88
	ds_write2_b32 v89, v39, v43 offset0:204 offset1:220
	v_mfma_f32_16x16x32_bf16 v[36:39], v[68:71], v[64:67], 0
	v_mfma_f32_16x16x32_bf16 v[40:43], v[68:71], v[60:63], 0
	s_nop 7
	ds_write2_b32 v88, v36, v40 offset0:96 offset1:112
	ds_write2_b32 v88, v37, v41 offset0:228 offset1:244
	ds_write2_b32 v89, v38, v42 offset0:104 offset1:120
	ds_write2_b32 v89, v39, v43 offset0:236 offset1:252
	s_waitcnt vmcnt(0) lgkmcnt(0)
	ds_read2st64_b32 v[36:37], v91 offset0:30 offset1:31
	ds_read2st64_b32 v[140:141], v84 offset0:28 offset1:29
	ds_read2st64_b32 v[142:143], v85 offset0:26 offset1:27
	ds_read2st64_b32 v[144:145], v92 offset0:24 offset1:25
	ds_read2st64_b32 v[146:147], v93 offset0:22 offset1:23
	ds_read2st64_b32 v[148:149], v94 offset0:20 offset1:21
	ds_read2st64_b32 v[150:151], v95 offset0:18 offset1:19
	ds_read2st64_b32 v[152:153], v96 offset0:16 offset1:17
	ds_read2st64_b32 v[154:155], v97 offset0:14 offset1:15
	ds_read2st64_b32 v[156:157], v98 offset0:12 offset1:13
	ds_read2st64_b32 v[158:159], v99 offset0:10 offset1:11
	ds_read2st64_b32 v[160:161], v100 offset0:8 offset1:9
	ds_read2st64_b32 v[162:163], v101 offset0:6 offset1:7
	ds_read2st64_b32 v[164:165], v102 offset0:4 offset1:5
	ds_read2_b32 v[166:167], v87 offset0:132 offset1:196
	ds_read2st64_b32 v[168:169], v87 offset1:1
	v_mov_b32_e32 v186, v103
	v_mov_b32_e32 v187, v108
	s_waitcnt lgkmcnt(0)
	v_mfma_f32_16x16x32_bf16 v[76:79], v[104:107], v[20:23], v[76:79]
	v_pk_fma_f32 v[184:185], v[82:83], v[186:187], v[36:37] op_sel:[1,1,0] op_sel_hi:[1,0,1] neg_lo:[1,0,0]
	v_pk_fma_f32 v[188:189], v[82:83], v[186:187], v[184:185] op_sel_hi:[0,1,1]
	v_cvt_pk_bf16_f32 v190, v188, v189
	ds_write_b16 v86, v190 offset:12528
	ds_write_b16_d16_hi v86, v190 offset:12656
	v_pk_fma_f32 v[184:185], v[82:83], v[188:189], v[140:141] op_sel:[1,1,0] op_sel_hi:[1,0,1] neg_lo:[1,0,0]
	v_pk_fma_f32 v[186:187], v[82:83], v[188:189], v[184:185] op_sel_hi:[0,1,1]
	v_cvt_pk_bf16_f32 v190, v186, v187
	ds_write_b16 v86, v190 offset:12256
	ds_write_b16_d16_hi v86, v190 offset:12384
	v_pk_fma_f32 v[184:185], v[82:83], v[186:187], v[142:143] op_sel:[1,1,0] op_sel_hi:[1,0,1] neg_lo:[1,0,0]
	v_pk_fma_f32 v[188:189], v[82:83], v[186:187], v[184:185] op_sel_hi:[0,1,1]
	v_cvt_pk_bf16_f32 v190, v188, v189
	ds_write_b16 v86, v190 offset:11984
	ds_write_b16_d16_hi v86, v190 offset:12112
	v_pk_fma_f32 v[184:185], v[82:83], v[188:189], v[144:145] op_sel:[1,1,0] op_sel_hi:[1,0,1] neg_lo:[1,0,0]
	v_pk_fma_f32 v[186:187], v[82:83], v[188:189], v[184:185] op_sel_hi:[0,1,1]
	v_cvt_pk_bf16_f32 v190, v186, v187
	ds_write_b16 v86, v190 offset:11712
	ds_write_b16_d16_hi v86, v190 offset:11840
	v_pk_fma_f32 v[184:185], v[82:83], v[186:187], v[146:147] op_sel:[1,1,0] op_sel_hi:[1,0,1] neg_lo:[1,0,0]
	v_pk_fma_f32 v[188:189], v[82:83], v[186:187], v[184:185] op_sel_hi:[0,1,1]
	v_cvt_pk_bf16_f32 v190, v188, v189
	ds_write_b16 v86, v190 offset:11440
	ds_write_b16_d16_hi v86, v190 offset:11568
	v_pk_fma_f32 v[184:185], v[82:83], v[188:189], v[148:149] op_sel:[1,1,0] op_sel_hi:[1,0,1] neg_lo:[1,0,0]
	v_pk_fma_f32 v[186:187], v[82:83], v[188:189], v[184:185] op_sel_hi:[0,1,1]
	v_cvt_pk_bf16_f32 v190, v186, v187
	ds_write_b16 v86, v190 offset:11168
	ds_write_b16_d16_hi v86, v190 offset:11296
	v_pk_fma_f32 v[184:185], v[82:83], v[186:187], v[150:151] op_sel:[1,1,0] op_sel_hi:[1,0,1] neg_lo:[1,0,0]
	v_pk_fma_f32 v[188:189], v[82:83], v[186:187], v[184:185] op_sel_hi:[0,1,1]
	v_cvt_pk_bf16_f32 v190, v188, v189
	ds_write_b16 v86, v190 offset:10896
	ds_write_b16_d16_hi v86, v190 offset:11024
	v_pk_fma_f32 v[184:185], v[82:83], v[188:189], v[152:153] op_sel:[1,1,0] op_sel_hi:[1,0,1] neg_lo:[1,0,0]
	v_pk_fma_f32 v[186:187], v[82:83], v[188:189], v[184:185] op_sel_hi:[0,1,1]
	v_cvt_pk_bf16_f32 v190, v186, v187
	ds_write_b16 v86, v190 offset:10624
	ds_write_b16_d16_hi v86, v190 offset:10752
	v_pk_fma_f32 v[184:185], v[82:83], v[186:187], v[154:155] op_sel:[1,1,0] op_sel_hi:[1,0,1] neg_lo:[1,0,0]
	v_pk_fma_f32 v[188:189], v[82:83], v[186:187], v[184:185] op_sel_hi:[0,1,1]
	v_cvt_pk_bf16_f32 v190, v188, v189
	ds_write_b16 v86, v190 offset:10352
	ds_write_b16_d16_hi v86, v190 offset:10480
	v_pk_fma_f32 v[184:185], v[82:83], v[188:189], v[156:157] op_sel:[1,1,0] op_sel_hi:[1,0,1] neg_lo:[1,0,0]
	v_pk_fma_f32 v[186:187], v[82:83], v[188:189], v[184:185] op_sel_hi:[0,1,1]
	v_cvt_pk_bf16_f32 v190, v186, v187
	ds_write_b16 v86, v190 offset:10080
	ds_write_b16_d16_hi v86, v190 offset:10208
	v_pk_fma_f32 v[184:185], v[82:83], v[186:187], v[158:159] op_sel:[1,1,0] op_sel_hi:[1,0,1] neg_lo:[1,0,0]
	v_pk_fma_f32 v[188:189], v[82:83], v[186:187], v[184:185] op_sel_hi:[0,1,1]
	v_cvt_pk_bf16_f32 v190, v188, v189
	ds_write_b16 v86, v190 offset:9808
	ds_write_b16_d16_hi v86, v190 offset:9936
	v_pk_fma_f32 v[184:185], v[82:83], v[188:189], v[160:161] op_sel:[1,1,0] op_sel_hi:[1,0,1] neg_lo:[1,0,0]
	v_pk_fma_f32 v[186:187], v[82:83], v[188:189], v[184:185] op_sel_hi:[0,1,1]
	v_cvt_pk_bf16_f32 v190, v186, v187
	ds_write_b16 v86, v190 offset:9536
	ds_write_b16_d16_hi v86, v190 offset:9664
	v_pk_fma_f32 v[184:185], v[82:83], v[186:187], v[162:163] op_sel:[1,1,0] op_sel_hi:[1,0,1] neg_lo:[1,0,0]
	v_pk_fma_f32 v[188:189], v[82:83], v[186:187], v[184:185] op_sel_hi:[0,1,1]
	v_cvt_pk_bf16_f32 v190, v188, v189
	ds_write_b16 v86, v190 offset:9264
	ds_write_b16_d16_hi v86, v190 offset:9392
	v_pk_fma_f32 v[184:185], v[82:83], v[188:189], v[164:165] op_sel:[1,1,0] op_sel_hi:[1,0,1] neg_lo:[1,0,0]
	v_pk_fma_f32 v[186:187], v[82:83], v[188:189], v[184:185] op_sel_hi:[0,1,1]
	v_cvt_pk_bf16_f32 v190, v186, v187
	ds_write_b16 v86, v190 offset:8992
	ds_write_b16_d16_hi v86, v190 offset:9120
	v_pk_fma_f32 v[184:185], v[82:83], v[186:187], v[166:167] op_sel:[1,1,0] op_sel_hi:[1,0,1] neg_lo:[1,0,0]
	v_pk_fma_f32 v[188:189], v[82:83], v[186:187], v[184:185] op_sel_hi:[0,1,1]
	v_cvt_pk_bf16_f32 v190, v188, v189
	ds_write_b16 v86, v190 offset:8720
	ds_write_b16_d16_hi v86, v190 offset:8848
	v_pk_fma_f32 v[184:185], v[82:83], v[188:189], v[168:169] op_sel:[1,1,0] op_sel_hi:[1,0,1] neg_lo:[1,0,0]
	v_pk_fma_f32 v[186:187], v[82:83], v[188:189], v[184:185] op_sel_hi:[0,1,1]
	v_mov_b32_e32 v36, v186
	v_mov_b32_e32 v37, v187
	v_cvt_pk_bf16_f32 v190, v186, v187
	ds_write_b16 v86, v190 offset:8448
	ds_write_b16_d16_hi v86, v190 offset:8576
	s_waitcnt vmcnt(0) lgkmcnt(0)
	ds_read_b128 v[36:39], v81 offset:8448
	s_waitcnt lgkmcnt(0)
	v_mfma_f32_16x16x32_bf16 v[32:35], v[36:39], v[32:35], 0
	ds_read_b128 v[36:39], v81 offset:8512
	s_waitcnt lgkmcnt(0)
	v_mfma_f32_16x16x32_bf16 v[28:31], v[36:39], v[28:31], v[32:35]
	s_nop 4
	ds_read_b128 v[32:35], v81 offset:8576
	s_waitcnt lgkmcnt(0)
	v_mfma_f32_16x16x32_bf16 v[24:27], v[32:35], v[24:27], v[28:31]
	s_nop 2
	ds_read_b128 v[28:31], v81 offset:8640
	s_waitcnt lgkmcnt(0)
	v_mfma_f32_16x16x32_bf16 v[20:23], v[28:31], v[20:23], v[24:27]
	s_nop 7
	v_pk_add_f32 v[24:25], v[0:1], v[20:21]
	v_and_or_b32 v0, v90, 15, v80
	v_add_u32_e32 v20, s6, v0
	v_ashrrev_i32_e32 v21, 31, v20
	v_lshrrev_b32_e32 v1, 2, v90
	v_lshl_add_u64 v[20:21], v[20:21], 2, s[76:77]
	v_and_b32_e32 v1, 12, v1
	global_load_dword v28, v[20:21], off
	v_add_u32_e32 v20, s8, v1
	v_ashrrev_i32_e32 v21, 31, v20
	v_ashrrev_i32_e32 v1, 31, v0
	v_lshlrev_b64 v[26:27], 9, v[20:21]
	v_lshl_add_u64 v[26:27], v[26:27], 0, v[0:1]
	v_lshl_add_u64 v[30:31], v[26:27], 1, s[36:37]
	global_load_ushort v29, v[30:31], off
	global_load_ushort v141, v[30:31], off offset:1024
	global_load_ushort v142, v[30:31], off offset:2048
	global_load_ushort v143, v[30:31], off offset:3072
	s_mov_b64 s[0:1], 0x4000
	v_lshl_add_u64 v[156:157], v[30:31], 0, s[0:1]
	global_load_ushort v144, v[156:157], off
	global_load_ushort v145, v[156:157], off offset:1024
	global_load_ushort v146, v[156:157], off offset:2048
	global_load_ushort v147, v[156:157], off offset:3072
	s_mov_b64 s[0:1], 0x8000
	v_lshl_add_u64 v[158:159], v[30:31], 0, s[0:1]
	global_load_ushort v148, v[158:159], off
	global_load_ushort v149, v[158:159], off offset:1024
	global_load_ushort v150, v[158:159], off offset:2048
	global_load_ushort v151, v[158:159], off offset:3072
	s_mov_b64 s[0:1], 0xc000
	v_lshl_add_u64 v[160:161], v[30:31], 0, s[0:1]
	global_load_ushort v152, v[160:161], off
	global_load_ushort v153, v[160:161], off offset:1024
	global_load_ushort v154, v[160:161], off offset:2048
	global_load_ushort v155, v[160:161], off offset:3072
	s_waitcnt vmcnt(0) lgkmcnt(0)
	v_lshlrev_b32_e32 v29, 16, v29
	v_fma_f32 v24, v28, v29, v24
	v_mul_f32_e32 v29, 0x3d372713, v24
	v_mul_f32_e32 v29, v24, v29
	v_fma_f32 v29, v24, v29, v24
	v_mul_f32_e32 v29, 0x3f4c422a, v29
	v_cmp_nlt_f32_e64 s[0:1], |v29|, s10
	s_and_saveexec_b64 s[2:3], s[0:1]
	s_xor_b64 s[0:1], exec, s[2:3]
	s_cbranch_execz .LBB0_1813
	v_add_f32_e64 v30, |v29|, |v29|
	v_mul_f32_e32 v31, 0x3fb8aa3b, v30
	v_rndne_f32_e32 v32, v31
	s_mov_b32 s2, 0x3fb8aa3b
	v_sub_f32_e32 v33, v31, v32
	v_fma_f32 v31, v30, s2, -v31
	v_fmac_f32_e32 v31, 0x32a5705f, v30
	v_add_f32_e32 v31, v33, v31
	v_cvt_i32_f32_e32 v32, v32
	v_exp_f32_e32 v31, v31
	s_mov_b32 s2, 0xc2ce8ed0
	v_cmp_ngt_f32_e32 vcc, s2, v30
	s_mov_b32 s2, 0x42b17218
	v_ldexp_f32 v31, v31, v32
	v_cndmask_b32_e32 v31, 0, v31, vcc
	v_cmp_nlt_f32_e32 vcc, s2, v30
	s_nop 1
	v_cndmask_b32_e32 v30, v235, v31, vcc
	v_add_f32_e32 v30, 1.0, v30
	v_rcp_f32_e32 v30, v30
	s_nop 0
	v_fma_f32 v30, v30, -2.0, 1.0
